# GLA core loads batched; GEMM LDS-DMA spread 1 per 2 MFMAs; shuffle reductions via permlane swap and DPP instead of ds_bpermute
# speedup vs baseline: 1.0620x; 1.0110x over previous
; #define MFMA32(a, b, c) __builtin_amdgcn_mfma_f32_32x32x16_bf16((a), (b), (c), 0, 0, 0)
; template <class AL, class EP>
; DI void gemm2(const int wave_s, const AL al, const u16* __restrict__ Wt, const int K, const int ntm, const int ntn, const EP ep, char* smem, const u16* zrow = nullptr) {
;     ...
;         const u16* ab = al.tilebase(tm, k0);
; #pragma unroll
;         for (int q = 0; q < 4; ++q) {
;           const u16* gp = (aoff[q] == 0xffffffffu) ? (zrow + scp * 8) : (ab + aoff[q]);
;           glds16(gp, sa + q * 1024);
;         }
;       } else {
; #pragma unroll
;         for (int i = 0; i < 4; ++i) ra[i] = al.load(tm, lrow + 64 * i, k0, lcp * 8);
;       }
;       const u16* wb = wbase + k0;
; #pragma unroll
;       for (int q = 0; q < 4; ++q) glds16(wb + woff[q], sa + 32768 + q * 1024);
;     ...
;       if (more) stage_issue(kt + 1, (kt + 1) & 1);
;       __builtin_amdgcn_sched_barrier(0);
;       const char* a = smem + (kt & 1) * G_STAGE_B + wm * 128 * 128;
;       const char* b = smem + (kt & 1) * G_STAGE_B + 32768 + wn * 64 * 128;
;       if constexpr (AL::DIRECT) {
;         bf16x8 af[2][4], bfr[2][2];
; #pragma unroll
;         for (int i = 0; i < 4; ++i) af[0][i] = *(const bf16x8*)(a + i * 4096 + foff[0]);
; #pragma unroll
;         for (int j = 0; j < 2; ++j) bfr[0][j] = *(const bf16x8*)(b + j * 4096 + foff[0]);
; #pragma unroll
;         for (int s = 0; s < 4; ++s) {
;           if (s < 3) {
; #pragma unroll
;             for (int i = 0; i < 4; ++i) af[(s + 1) & 1][i] = *(const bf16x8*)(a + i * 4096 + foff[s + 1]);
; #pragma unroll
;             for (int j = 0; j < 2; ++j) bfr[(s + 1) & 1][j] = *(const bf16x8*)(b + j * 4096 + foff[s + 1]);
;           }
;           __builtin_amdgcn_sched_barrier(0);
;           __builtin_amdgcn_s_setprio(1);
; #pragma unroll
;           for (int i = 0; i < 4; ++i) {
;             acc[i][0] = MFMA32(af[s & 1][i], bfr[s & 1][0], acc[i][0]);
;             acc[i][1] = MFMA32(af[s & 1][i], bfr[s & 1][1], acc[i][1]);
;           }
;           __builtin_amdgcn_s_setprio(0);
;           __builtin_amdgcn_sched_barrier(0);
;         }
.Lrot0_loop:
	s_setprio 1
	s_waitcnt lgkmcnt(6)
	v_mfma_f32_32x32x16_bf16 v[114:129], v[182:185], v[198:201], v[114:129]
	v_mfma_f32_32x32x16_bf16 v[98:113], v[182:185], v[202:205], v[98:113]
	v_mfma_f32_32x32x16_bf16 v[82:97], v[186:189], v[198:201], v[82:97]
	v_mfma_f32_32x32x16_bf16 v[66:81], v[186:189], v[202:205], v[66:81]
	v_mfma_f32_32x32x16_bf16 v[50:65], v[190:193], v[198:201], v[50:65]
	v_mfma_f32_32x32x16_bf16 v[34:49], v[190:193], v[202:205], v[34:49]
	v_mfma_f32_32x32x16_bf16 v[18:33], v[194:197], v[198:201], v[18:33]
	v_mfma_f32_32x32x16_bf16 v[2:17], v[194:197], v[202:205], v[2:17]
	s_setprio 0
	v_add_u32_e32 v0, s10, v175
	ds_read_b128 v[182:185], v0
	ds_read_b128 v[186:189], v0 offset:4096
	ds_read_b128 v[190:193], v0 offset:8192
	ds_read_b128 v[194:197], v0 offset:12288
	v_add_u32_e32 v0, s7, v175
	ds_read_b128 v[198:201], v0 offset:32768
	ds_read_b128 v[202:205], v0 offset:36864
	s_setprio 1
	s_waitcnt lgkmcnt(6)
	v_mfma_f32_32x32x16_bf16 v[114:129], v[206:209], v[222:225], v[114:129]
	v_mfma_f32_32x32x16_bf16 v[98:113], v[206:209], v[226:229], v[98:113]
	v_mfma_f32_32x32x16_bf16 v[82:97], v[210:213], v[222:225], v[82:97]
	v_mfma_f32_32x32x16_bf16 v[66:81], v[210:213], v[226:229], v[66:81]
	v_mfma_f32_32x32x16_bf16 v[50:65], v[214:217], v[222:225], v[50:65]
	v_mfma_f32_32x32x16_bf16 v[34:49], v[214:217], v[226:229], v[34:49]
	v_mfma_f32_32x32x16_bf16 v[18:33], v[218:221], v[222:225], v[18:33]
	v_mfma_f32_32x32x16_bf16 v[2:17], v[218:221], v[226:229], v[2:17]
	s_setprio 0
	v_add_u32_e32 v0, s10, v172
	ds_read_b128 v[206:209], v0
	ds_read_b128 v[210:213], v0 offset:4096
	ds_read_b128 v[214:217], v0 offset:8192
	ds_read_b128 v[218:221], v0 offset:12288
	v_add_u32_e32 v0, s7, v172
	ds_read_b128 v[222:225], v0 offset:32768
	ds_read_b128 v[226:229], v0 offset:36864
	s_add_i32 s5, s5, 0x10000
	s_and_b32 s10, s5, 0x10000
	s_add_i32 s7, s10, s17
	s_add_i32 s10, s10, s16
	s_cmp_eq_u32 s5, 0xf0000
	s_waitcnt vmcnt(0) lgkmcnt(0)
	s_barrier
	s_cbranch_scc1 .Lrot0_tail
	s_setprio 1
	s_add_i32 m0, s5, 0x10000
	s_and_b32 m0, m0, 0x10000
	s_add_i32 m0, m0, s15
	v_mfma_f32_32x32x16_bf16 v[114:129], v[182:185], v[198:201], v[114:129]
	global_load_lds_dwordx4 v[176:177], off
	v_lshl_add_u64 v[176:177], v[176:177], 0, s[8:9]
	s_add_i32 m0, m0, 0x400
	v_mfma_f32_32x32x16_bf16 v[98:113], v[182:185], v[202:205], v[98:113]
	v_mfma_f32_32x32x16_bf16 v[82:97], v[186:189], v[198:201], v[82:97]
	global_load_lds_dwordx4 v[168:169], off
	v_lshl_add_u64 v[168:169], v[168:169], 0, s[8:9]
	s_add_i32 m0, m0, 0x400
	v_mfma_f32_32x32x16_bf16 v[66:81], v[186:189], v[202:205], v[66:81]
	v_mfma_f32_32x32x16_bf16 v[50:65], v[190:193], v[198:201], v[50:65]
	global_load_lds_dwordx4 v[166:167], off
	v_lshl_add_u64 v[166:167], v[166:167], 0, s[8:9]
	s_add_i32 m0, m0, 0x400
	v_mfma_f32_32x32x16_bf16 v[34:49], v[190:193], v[202:205], v[34:49]
	v_mfma_f32_32x32x16_bf16 v[18:33], v[194:197], v[198:201], v[18:33]
	global_load_lds_dwordx4 v[164:165], off
	v_lshl_add_u64 v[164:165], v[164:165], 0, s[8:9]
	s_add_i32 m0, m0, 0x7400
	v_mfma_f32_32x32x16_bf16 v[2:17], v[194:197], v[202:205], v[2:17]
	s_setprio 0
	v_add_u32_e32 v0, s10, v179
	ds_read_b128 v[182:185], v0
	ds_read_b128 v[186:189], v0 offset:4096
	ds_read_b128 v[190:193], v0 offset:8192
	ds_read_b128 v[194:197], v0 offset:12288
	v_add_u32_e32 v0, s7, v179
	ds_read_b128 v[198:201], v0 offset:32768
	ds_read_b128 v[202:205], v0 offset:36864
	s_setprio 1
	v_mfma_f32_32x32x16_bf16 v[114:129], v[206:209], v[222:225], v[114:129]
	global_load_lds_dwordx4 v[162:163], off
	v_lshl_add_u64 v[162:163], v[162:163], 0, s[8:9]
	s_add_i32 m0, m0, 0x400
	v_mfma_f32_32x32x16_bf16 v[98:113], v[206:209], v[226:229], v[98:113]
	v_mfma_f32_32x32x16_bf16 v[82:97], v[210:213], v[222:225], v[82:97]
	global_load_lds_dwordx4 v[160:161], off
	v_lshl_add_u64 v[160:161], v[160:161], 0, s[8:9]
	s_add_i32 m0, m0, 0x400
	v_mfma_f32_32x32x16_bf16 v[66:81], v[210:213], v[226:229], v[66:81]
	v_mfma_f32_32x32x16_bf16 v[50:65], v[214:217], v[222:225], v[50:65]
	global_load_lds_dwordx4 v[158:159], off
	v_lshl_add_u64 v[158:159], v[158:159], 0, s[8:9]
	s_add_i32 m0, m0, 0x400
	v_mfma_f32_32x32x16_bf16 v[34:49], v[214:217], v[226:229], v[34:49]
	v_mfma_f32_32x32x16_bf16 v[18:33], v[218:221], v[222:225], v[18:33]
	global_load_lds_dwordx4 v[156:157], off
	v_lshl_add_u64 v[156:157], v[156:157], 0, s[8:9]
	v_mfma_f32_32x32x16_bf16 v[2:17], v[218:221], v[226:229], v[2:17]
	s_setprio 0
	v_add_u32_e32 v0, s10, v178
	ds_read_b128 v[206:209], v0
	ds_read_b128 v[210:213], v0 offset:4096
	ds_read_b128 v[214:217], v0 offset:8192
	ds_read_b128 v[218:221], v0 offset:12288
	v_add_u32_e32 v0, s7, v178
	ds_read_b128 v[222:225], v0 offset:32768
	ds_read_b128 v[226:229], v0 offset:36864
	s_branch .Lrot0_loop

; #define MFMA32(a, b, c) __builtin_amdgcn_mfma_f32_32x32x16_bf16((a), (b), (c), 0, 0, 0)
; template <class AL, class EP>
; DI void gemm2(const int wave_s, const AL al, const u16* __restrict__ Wt, const int K, const int ntm, const int ntn, const EP ep, char* smem, const u16* zrow = nullptr) {
;     ...
;         const u16* ab = al.tilebase(tm, k0);
; #pragma unroll
;         for (int q = 0; q < 4; ++q) {
;           const u16* gp = (aoff[q] == 0xffffffffu) ? (zrow + scp * 8) : (ab + aoff[q]);
;           glds16(gp, sa + q * 1024);
;         }
;       } else {
; #pragma unroll
;         for (int i = 0; i < 4; ++i) ra[i] = al.load(tm, lrow + 64 * i, k0, lcp * 8);
;       }
;       const u16* wb = wbase + k0;
; #pragma unroll
;       for (int q = 0; q < 4; ++q) glds16(wb + woff[q], sa + 32768 + q * 1024);
;     ...
;       if (more) stage_issue(kt + 1, (kt + 1) & 1);
;       __builtin_amdgcn_sched_barrier(0);
;       const char* a = smem + (kt & 1) * G_STAGE_B + wm * 128 * 128;
;       const char* b = smem + (kt & 1) * G_STAGE_B + 32768 + wn * 64 * 128;
;       if constexpr (AL::DIRECT) {
;         bf16x8 af[2][4], bfr[2][2];
; #pragma unroll
;         for (int i = 0; i < 4; ++i) af[0][i] = *(const bf16x8*)(a + i * 4096 + foff[0]);
; #pragma unroll
;         for (int j = 0; j < 2; ++j) bfr[0][j] = *(const bf16x8*)(b + j * 4096 + foff[0]);
; #pragma unroll
;         for (int s = 0; s < 4; ++s) {
;           if (s < 3) {
; #pragma unroll
;             for (int i = 0; i < 4; ++i) af[(s + 1) & 1][i] = *(const bf16x8*)(a + i * 4096 + foff[s + 1]);
; #pragma unroll
;             for (int j = 0; j < 2; ++j) bfr[(s + 1) & 1][j] = *(const bf16x8*)(b + j * 4096 + foff[s + 1]);
;           }
;           __builtin_amdgcn_sched_barrier(0);
;           __builtin_amdgcn_s_setprio(1);
; #pragma unroll
;           for (int i = 0; i < 4; ++i) {
;             acc[i][0] = MFMA32(af[s & 1][i], bfr[s & 1][0], acc[i][0]);
;             acc[i][1] = MFMA32(af[s & 1][i], bfr[s & 1][1], acc[i][1]);
;           }
;           __builtin_amdgcn_s_setprio(0);
;           __builtin_amdgcn_sched_barrier(0);
;         }
.Lrot1_loop:
	s_setprio 1
	s_waitcnt lgkmcnt(6)
	v_mfma_f32_32x32x16_bf16 v[114:129], v[182:185], v[198:201], v[114:129]
	v_mfma_f32_32x32x16_bf16 v[98:113], v[182:185], v[202:205], v[98:113]
	v_mfma_f32_32x32x16_bf16 v[82:97], v[186:189], v[198:201], v[82:97]
	v_mfma_f32_32x32x16_bf16 v[66:81], v[186:189], v[202:205], v[66:81]
	v_mfma_f32_32x32x16_bf16 v[50:65], v[190:193], v[198:201], v[50:65]
	v_mfma_f32_32x32x16_bf16 v[34:49], v[190:193], v[202:205], v[34:49]
	v_mfma_f32_32x32x16_bf16 v[18:33], v[194:197], v[198:201], v[18:33]
	v_mfma_f32_32x32x16_bf16 v[2:17], v[194:197], v[202:205], v[2:17]
	s_setprio 0
	v_add_u32_e32 v0, s10, v175
	ds_read_b128 v[182:185], v0
	ds_read_b128 v[186:189], v0 offset:4096
	ds_read_b128 v[190:193], v0 offset:8192
	ds_read_b128 v[194:197], v0 offset:12288
	v_add_u32_e32 v0, s7, v175
	ds_read_b128 v[198:201], v0 offset:32768
	ds_read_b128 v[202:205], v0 offset:36864
	s_setprio 1
	s_waitcnt lgkmcnt(6)
	v_mfma_f32_32x32x16_bf16 v[114:129], v[206:209], v[222:225], v[114:129]
	v_mfma_f32_32x32x16_bf16 v[98:113], v[206:209], v[226:229], v[98:113]
	v_mfma_f32_32x32x16_bf16 v[82:97], v[210:213], v[222:225], v[82:97]
	v_mfma_f32_32x32x16_bf16 v[66:81], v[210:213], v[226:229], v[66:81]
	v_mfma_f32_32x32x16_bf16 v[50:65], v[214:217], v[222:225], v[50:65]
	v_mfma_f32_32x32x16_bf16 v[34:49], v[214:217], v[226:229], v[34:49]
	v_mfma_f32_32x32x16_bf16 v[18:33], v[218:221], v[222:225], v[18:33]
	v_mfma_f32_32x32x16_bf16 v[2:17], v[218:221], v[226:229], v[2:17]
	s_setprio 0
	v_add_u32_e32 v0, s10, v172
	ds_read_b128 v[206:209], v0
	ds_read_b128 v[210:213], v0 offset:4096
	ds_read_b128 v[214:217], v0 offset:8192
	ds_read_b128 v[218:221], v0 offset:12288
	v_add_u32_e32 v0, s7, v172
	ds_read_b128 v[222:225], v0 offset:32768
	ds_read_b128 v[226:229], v0 offset:36864
	s_add_i32 s5, s5, 0x10000
	s_and_b32 s10, s5, 0x10000
	s_add_i32 s7, s10, s15
	s_add_i32 s10, s10, s14
	s_cmp_eq_u32 s5, 0xf0000
	s_waitcnt vmcnt(0) lgkmcnt(0)
	s_barrier
	s_cbranch_scc1 .Lrot1_tail
	s_setprio 1
	s_add_i32 m0, s5, 0x10000
	s_and_b32 m0, m0, 0x10000
	s_add_i32 m0, m0, s13
	v_mfma_f32_32x32x16_bf16 v[114:129], v[182:185], v[198:201], v[114:129]
	global_load_lds_dwordx4 v[176:177], off
	v_lshl_add_u64 v[176:177], v[176:177], 0, s[8:9]
	s_add_i32 m0, m0, 0x400
	v_mfma_f32_32x32x16_bf16 v[98:113], v[182:185], v[202:205], v[98:113]
	v_mfma_f32_32x32x16_bf16 v[82:97], v[186:189], v[198:201], v[82:97]
	global_load_lds_dwordx4 v[168:169], off
	v_lshl_add_u64 v[168:169], v[168:169], 0, s[8:9]
	s_add_i32 m0, m0, 0x400
	v_mfma_f32_32x32x16_bf16 v[66:81], v[186:189], v[202:205], v[66:81]
	v_mfma_f32_32x32x16_bf16 v[50:65], v[190:193], v[198:201], v[50:65]
	global_load_lds_dwordx4 v[166:167], off
	v_lshl_add_u64 v[166:167], v[166:167], 0, s[8:9]
	s_add_i32 m0, m0, 0x400
	v_mfma_f32_32x32x16_bf16 v[34:49], v[190:193], v[202:205], v[34:49]
	v_mfma_f32_32x32x16_bf16 v[18:33], v[194:197], v[198:201], v[18:33]
	global_load_lds_dwordx4 v[164:165], off
	v_lshl_add_u64 v[164:165], v[164:165], 0, s[8:9]
	s_add_i32 m0, m0, 0x7400
	v_mfma_f32_32x32x16_bf16 v[2:17], v[194:197], v[202:205], v[2:17]
	s_setprio 0
	v_add_u32_e32 v0, s10, v179
	ds_read_b128 v[182:185], v0
	ds_read_b128 v[186:189], v0 offset:4096
	ds_read_b128 v[190:193], v0 offset:8192
	ds_read_b128 v[194:197], v0 offset:12288
	v_add_u32_e32 v0, s7, v179
	ds_read_b128 v[198:201], v0 offset:32768
	ds_read_b128 v[202:205], v0 offset:36864
	s_setprio 1
	v_mfma_f32_32x32x16_bf16 v[114:129], v[206:209], v[222:225], v[114:129]
	global_load_lds_dwordx4 v[162:163], off
	v_lshl_add_u64 v[162:163], v[162:163], 0, s[8:9]
	s_add_i32 m0, m0, 0x400
	v_mfma_f32_32x32x16_bf16 v[98:113], v[206:209], v[226:229], v[98:113]
	v_mfma_f32_32x32x16_bf16 v[82:97], v[210:213], v[222:225], v[82:97]
	global_load_lds_dwordx4 v[160:161], off
	v_lshl_add_u64 v[160:161], v[160:161], 0, s[8:9]
	s_add_i32 m0, m0, 0x400
	v_mfma_f32_32x32x16_bf16 v[66:81], v[210:213], v[226:229], v[66:81]
	v_mfma_f32_32x32x16_bf16 v[50:65], v[214:217], v[222:225], v[50:65]
	global_load_lds_dwordx4 v[158:159], off
	v_lshl_add_u64 v[158:159], v[158:159], 0, s[8:9]
	s_add_i32 m0, m0, 0x400
	v_mfma_f32_32x32x16_bf16 v[34:49], v[214:217], v[226:229], v[34:49]
	v_mfma_f32_32x32x16_bf16 v[18:33], v[218:221], v[222:225], v[18:33]
	global_load_lds_dwordx4 v[156:157], off
	v_lshl_add_u64 v[156:157], v[156:157], 0, s[8:9]
	v_mfma_f32_32x32x16_bf16 v[2:17], v[218:221], v[226:229], v[2:17]
	s_setprio 0
	v_add_u32_e32 v0, s10, v178
	ds_read_b128 v[206:209], v0
	ds_read_b128 v[210:213], v0 offset:4096
	ds_read_b128 v[214:217], v0 offset:8192
	ds_read_b128 v[218:221], v0 offset:12288
	v_add_u32_e32 v0, s7, v178
	ds_read_b128 v[222:225], v0 offset:32768
	ds_read_b128 v[226:229], v0 offset:36864
	s_branch .Lrot1_loop

; DI float bflo(unsigned u) { return __uint_as_float(u << 16); }
; DI float bfhi(unsigned u) { return __uint_as_float(u & 0xffff0000u); }
; __global__ void __launch_bounds__(NTHR) mega(Params p) {
;     ...
;         for (int t = blockIdx.x * 8 + wv; t < TOK; t += gridDim.x * 8) {
;           const u16* row = CIN + (size_t)t * 768;
;           const uint2 c0 = *(const uint2*)(row + lane * 4);
;           uint2 c1 = make_uint2(0u, 0u);
;           if (lane < 32) c1 = *(const uint2*)(row + 256 + lane * 4);
;           const uint2 k0 = *(const uint2*)(row + 384 + lane * 4);
;           const float a0 = bflo(c0.x), a1 = bfhi(c0.x), a2 = bflo(c0.y), a3 = bfhi(c0.y);
;           const float b0 = bflo(c1.x), b1 = bfhi(c1.x), b2 = bflo(c1.y), b3 = bfhi(c1.y);
;           const float d0 = bflo(k0.x), d1 = bfhi(k0.x), d2 = bflo(k0.y), d3 = bfhi(k0.y);
;           const float ssq = wsum(a0 * a0 + a1 * a1 + a2 * a2 + a3 * a3 + b0 * b0 + b1 * b1 + b2 * b2 + b3 * b3);
;           const float ssk = wsum(d0 * d0 + d1 * d1 + d2 * d2 + d3 * d3);
;           const float rq = rsqrtf(ssq * (1.f / 384.f) + 1e-6f), rk = rsqrtf(ssk * (1.f / 256.f) + 1e-6f);
;           {
;             const float4 g = *(const float4*)(qn + lane * 4);
;             uint2 o; o.x = pack2(a0 * rq * g.x, a1 * rq * g.y); o.y = pack2(a2 * rq * g.z, a3 * rq * g.w);
;             *(uint2*)(CQN + (size_t)t * 384 + lane * 4) = o;
;           }
;           if (lane < 32) {
;             const float4 g = *(const float4*)(qn + 256 + lane * 4);
;             uint2 o; o.x = pack2(b0 * rq * g.x, b1 * rq * g.y); o.y = pack2(b2 * rq * g.z, b3 * rq * g.w);
;             *(uint2*)(CQN + (size_t)t * 384 + 256 + lane * 4) = o;
;           }
;           {
;             const float4 g = *(const float4*)(kvn + lane * 4);
;             uint2 o; o.x = pack2(d0 * rk * g.x, d1 * rk * g.y); o.y = pack2(d2 * rk * g.z, d3 * rk * g.w);
;             *(uint2*)(CKVN + (size_t)t * 256 + lane * 4) = o;
;           }
.LBB0_1978:
	s_or_b64 exec, exec, s[6:7]
	flat_load_dwordx2 v[28:29], v[18:19] offset:768
	flat_load_dwordx4 v[32:35], v[2:3]
	s_waitcnt vmcnt(0) lgkmcnt(0)
	v_and_b32_e32 v37, 0xffff0000, v20
	v_lshlrev_b32_e32 v36, 16, v20
	v_mul_f32_e32 v0, v37, v37
	v_lshlrev_b32_e32 v38, 16, v21
	v_and_b32_e32 v39, 0xffff0000, v21
	v_pk_fma_f32 v[26:27], v[36:37], v[36:37], v[0:1] op_sel_hi:[1,1,0]
	v_lshlrev_b32_e32 v20, 16, v22
	v_and_b32_e32 v21, 0xffff0000, v22
	v_mul_f32_e32 v22, v39, v39
	v_pk_fma_f32 v[26:27], v[38:39], v[38:39], v[26:27]
	v_lshlrev_b32_e32 v24, 16, v23
	v_and_b32_e32 v25, 0xffff0000, v23
	v_pk_add_f32 v[22:23], v[22:23], v[26:27] op_sel_hi:[0,1]
	v_pk_mul_f32 v[30:31], v[20:21], v[20:21]
	v_pk_fma_f32 v[44:45], v[20:21], v[20:21], v[22:23]
	v_pk_mul_f32 v[40:41], v[24:25], v[24:25]
	s_ashr_i32 s15, s14, 31
	v_mov_b32_e32 v43, v40
	v_lshlrev_b32_e32 v26, 16, v28
	v_and_b32_e32 v27, 0xffff0000, v28
	v_lshlrev_b32_e32 v22, 16, v29
	v_and_b32_e32 v23, 0xffff0000, v29
	v_pk_mul_f32 v[28:29], v[26:27], v[26:27]
	v_pk_mul_f32 v[46:47], v[22:23], v[22:23]
	v_mov_b32_e32 v30, v28
	v_pk_mov_b32 v[28:29], v[28:29], v[44:45] op_sel:[1,0]
	v_mov_b32_e32 v42, v46
	v_pk_add_f32 v[28:29], v[30:31], v[28:29]
	v_mov_b32_e32 v40, v47
	v_pk_add_f32 v[28:29], v[28:29], v[42:43]
	s_nop 0
	v_pk_add_f32 v[28:29], v[40:41], v[28:29]
	v_mov_b32_e32 v30, v28
	s_nop 1
	v_permlane32_swap_b32_e32 v28, v30
	v_mov_b32_e32 v31, v29
	s_nop 1
	v_permlane32_swap_b32_e32 v29, v31
	s_waitcnt lgkmcnt(0)
	v_pk_add_f32 v[28:29], v[28:29], v[30:31]
	v_mov_b32_e32 v30, v28
	s_nop 1
	v_permlane16_swap_b32_e32 v28, v30
	v_mov_b32_e32 v31, v29
	s_nop 1
	v_permlane16_swap_b32_e32 v29, v31
	s_waitcnt lgkmcnt(0)
	v_pk_add_f32 v[28:29], v[28:29], v[30:31]
	s_nop 1
	v_mov_b32_dpp v30, v28 row_ror:8 row_mask:0xf bank_mask:0xf
	s_nop 1
	v_mov_b32_dpp v31, v29 row_ror:8 row_mask:0xf bank_mask:0xf
	s_waitcnt lgkmcnt(0)
	v_pk_add_f32 v[28:29], v[28:29], v[30:31]
	s_nop 1
	v_mov_b32_dpp v30, v28 row_ror:4 row_mask:0xf bank_mask:0xf
	s_nop 1
	v_mov_b32_dpp v31, v29 row_ror:4 row_mask:0xf bank_mask:0xf
	s_waitcnt lgkmcnt(0)
	v_pk_add_f32 v[28:29], v[28:29], v[30:31]
	s_nop 1
	v_mov_b32_dpp v30, v28 row_ror:2 row_mask:0xf bank_mask:0xf
	s_nop 1
	v_mov_b32_dpp v31, v29 row_ror:2 row_mask:0xf bank_mask:0xf
	s_waitcnt lgkmcnt(0)
	v_pk_add_f32 v[28:29], v[28:29], v[30:31]
	s_nop 1
	v_mov_b32_dpp v30, v28 row_ror:1 row_mask:0xf bank_mask:0xf
	s_nop 1
	v_mov_b32_dpp v31, v29 row_ror:1 row_mask:0xf bank_mask:0xf
	s_waitcnt lgkmcnt(0)
	v_pk_add_f32 v[28:29], v[28:29], v[30:31]
	s_nop 0
	v_pk_fma_f32 v[28:29], v[28:29], s[36:37], v[170:171] op_sel_hi:[1,1,0]
	s_nop 0
	v_mul_f32_e32 v0, 0x4b800000, v29
	v_cmp_gt_f32_e64 s[8:9], s31, v29
	v_cmp_gt_f32_e64 s[6:7], s31, v28
	s_nop 0
	v_cndmask_b32_e64 v0, v29, v0, s[8:9]
	v_rsq_f32_e32 v0, v0
	s_nop 0
	v_mul_f32_e32 v29, 0x45800000, v0
	v_cndmask_b32_e64 v30, v0, v29, s[8:9]
	v_pk_mul_f32 v[36:37], v[30:31], v[36:37] op_sel_hi:[0,1]
	v_pk_mul_f32 v[38:39], v[30:31], v[38:39] op_sel_hi:[0,1]
	v_pk_mul_f32 v[32:33], v[32:33], v[36:37]
	v_pk_mul_f32 v[34:35], v[34:35], v[38:39]
	v_mov_b32_e32 v0, 0x300
	v_cvt_pk_bf16_f32 v36, v32, v33
	v_cvt_pk_bf16_f32 v37, v34, v35
	v_mad_i64_i32 v[32:33], s[8:9], s14, v0, v[12:13]
	flat_store_dwordx2 v[32:33], v[36:37]
	s_and_saveexec_b64 s[8:9], vcc
	s_cbranch_execz .LBB0_1980
	flat_load_dwordx4 v[34:37], v[2:3] offset:1024
	v_mov_b32_e32 v31, v30
	v_pk_mul_f32 v[20:21], v[30:31], v[20:21]
	v_pk_mul_f32 v[24:25], v[30:31], v[24:25]
	s_waitcnt vmcnt(0) lgkmcnt(0)
	v_pk_mul_f32 v[20:21], v[20:21], v[34:35]
	v_pk_mul_f32 v[24:25], v[24:25], v[36:37]
	v_cvt_pk_bf16_f32 v20, v20, v21
	v_cvt_pk_bf16_f32 v21, v24, v25
	flat_store_dwordx2 v[32:33], v[20:21] offset:512

; #define MFMA32(a, b, c) __builtin_amdgcn_mfma_f32_32x32x16_bf16((a), (b), (c), 0, 0, 0)
; DI int crow(int i, int h) { return (i & 3) + 8 * (i >> 2) + 4 * h; }
; DI void mla_attention(const int wave_s, const u16* __restrict__ QC, const u16* __restrict__ KF, const u16* __restrict__ Vt, u16* __restrict__ O, char* smem) {
;     ...
;       if (more) {
;         const u16* kb2 = kbase + (size_t)(jt + 1) * 64 * 1536;
;         k0r = *(const uint4*)(kb2 + (unsigned)(kr0 * 1536 + kc0));
;         if (tid < 256) k1r = *(const uint4*)(kb2 + (unsigned)(kr1 * 1536 + kc1));
;         vrr = *(const uint4*)(vbase + (jt + 1) * 64 + (unsigned)(vr * SEQ + vc));
;       }
;       const u16* kst = Ks + (jt & 1) * 64 * MK_RS;
;       const u16* vst = Vs + (jt & 1) * 64 * MV_RS;
; #pragma unroll
;       for (int half = 0; half < 2; ++half) {
;         const int ks = jt * 64 + half * 32;
;         if (ks <= q0) {
;           const u16* kp = kst + (half * 32 + r) * MK_RS + 8 * h;
;           f32x16 st = zero16();
; #pragma unroll
;           for (int s = 0; s < 6; ++s) {
;             const bf16x8 kf = *(const bf16x8*)(kp + 16 * s);
;             st = MFMA32(kf, qf[s], st);
;           }
;           if (ks == q0) {
; #pragma unroll
;             for (int i = 0; i < 16; ++i)
;               if (crow(i, h) > r) st[i] = -1e30f;
;     ...
;             const uint2 a0 = *(const uint2*)(vp + 16 * s2), a1 = *(const uint2*)(vp + 16 * s2 + 8);
;             const uint2 b0 = *(const uint2*)(vp + 32 * MV_RS + 16 * s2), b1 = *(const uint2*)(vp + 32 * MV_RS + 16 * s2 + 8);
.LBB0_2392:
	v_lshl_add_u64 v[34:35], s[86:87], 0, v[108:109]
	s_waitcnt vmcnt(0)
	global_load_dwordx4 v[74:77], v[34:35], off
	s_and_saveexec_b64 s[42:43], s[4:5]
	s_cbranch_execz .LBB0_2394
	v_lshl_add_u64 v[34:35], s[86:87], 0, v[106:107]
	v_add_co_u32_e32 v34, vcc, 0x12830000, v34
	s_nop 1
	v_addc_co_u32_e32 v35, vcc, 0, v35, vcc
	global_load_dwordx4 v[78:81], v[34:35], off
.LBB0_2394:
	s_or_b64 exec, exec, s[42:43]
	v_lshl_add_u64 v[34:35], s[86:87], 0, v[110:111]
	v_add_co_u32_e32 v34, vcc, 0x18800000, v34
	s_nop 1
	v_addc_co_u32_e32 v35, vcc, 0, v35, vcc
	global_load_dwordx4 v[82:85], v[34:35], off offset:128
.LBB0_2395:
	s_and_b32 s42, s94, 64
	s_mul_i32 s43, s42, 0xd0
	v_add_u32_e32 v0, s43, v114
	s_mulk_i32 s42, 0x88
	s_cmp_gt_i32 s94, s93
	v_add_u32_e32 v120, v0, v116
	s_cbranch_scc1 .LBB0_2402
	ds_read_b128 v[34:37], v120
	ds_read_b128 v[122:125], v120 offset:32
	ds_read_b128 v[176:179], v120 offset:64
	ds_read_b128 v[180:183], v120 offset:96
	ds_read_b128 v[184:187], v120 offset:128
	ds_read_b128 v[188:191], v120 offset:160
	v_add_u32_e32 v209, s42, v115
	v_add_u32_e32 v208, 0x6800, v209
	v_add_u32_e32 v209, 0x7800, v209
	ds_read2_b64 v[192:195], v208 offset1:2
	ds_read2_b64 v[196:199], v209 offset0:32 offset1:34
	ds_read2_b64 v[200:203], v208 offset0:4 offset1:6
	ds_read2_b64 v[204:207], v209 offset0:36 offset1:38
	s_cmp_lg_u32 s93, s94
	s_waitcnt lgkmcnt(8)
	v_mfma_f32_32x32x16_bf16 v[34:49], v[34:37], v[50:53], 0
	v_mfma_f32_32x32x16_bf16 v[34:49], v[122:125], v[54:57], v[34:49]
	s_waitcnt lgkmcnt(7)
	v_mfma_f32_32x32x16_bf16 v[34:49], v[176:179], v[58:61], v[34:49]
	s_waitcnt lgkmcnt(6)
	v_mfma_f32_32x32x16_bf16 v[34:49], v[180:183], v[62:65], v[34:49]
	s_waitcnt lgkmcnt(5)
	v_mfma_f32_32x32x16_bf16 v[34:49], v[184:187], v[66:69], v[34:49]
	s_waitcnt lgkmcnt(4)
	v_mfma_f32_32x32x16_bf16 v[34:49], v[188:191], v[70:73], v[34:49]
	s_cbranch_scc1 .LBB0_2398
	s_nop 10
	v_cndmask_b32_e64 v0, v34, v245, s[6:7]
	v_cndmask_b32_e64 v35, v245, v35, s[8:9]
	v_cndmask_b32_e64 v34, v0, v34, s[8:9]
	v_cndmask_b32_e64 v36, v36, v245, s[10:11]
	v_cndmask_b32_e64 v37, v37, v245, s[12:13]
	v_cndmask_b32_e64 v38, v38, v245, s[14:15]
	v_cndmask_b32_e64 v39, v39, v245, s[16:17]
	v_cndmask_b32_e64 v40, v40, v245, s[18:19]
	v_cndmask_b32_e64 v41, v41, v245, s[20:21]
	v_cndmask_b32_e64 v42, v42, v245, s[22:23]
	v_cndmask_b32_e64 v43, v43, v245, s[24:25]
	v_cndmask_b32_e64 v44, v44, v245, s[26:27]
	v_cndmask_b32_e64 v45, v45, v245, s[28:29]
	v_cndmask_b32_e64 v46, v46, v245, s[30:31]
	v_cndmask_b32_e64 v47, v47, v245, s[34:35]
	v_cndmask_b32_e64 v48, v48, v245, s[36:37]
	v_cndmask_b32_e64 v49, v49, v245, s[38:39]

; #define MFMA32(a, b, c) __builtin_amdgcn_mfma_f32_32x32x16_bf16((a), (b), (c), 0, 0, 0)
; DI void mla_attention(const int wave_s, const u16* __restrict__ QC, const u16* __restrict__ KF, const u16* __restrict__ Vt, u16* __restrict__ O, char* smem) {
;     ...
;           bf16x8 pf[2];
; #pragma unroll
;           for (int s2 = 0; s2 < 2; ++s2) {
;             uint4 u;
;             u.x = pack2(st[8 * s2 + 0], st[8 * s2 + 1]);
;             u.y = pack2(st[8 * s2 + 2], st[8 * s2 + 3]);
;             u.z = pack2(st[8 * s2 + 4], st[8 * s2 + 5]);
;             u.w = pack2(st[8 * s2 + 6], st[8 * s2 + 7]);
;             pf[s2] = __builtin_bit_cast(bf16x8, u);
;           }
;           const u16* vp = vst + r * MV_RS + half * 32 + 4 * h;
; #pragma unroll
;           for (int s2 = 0; s2 < 2; ++s2) {
;             uint4 u0, u1;
;             const uint2 a0 = *(const uint2*)(vp + 16 * s2), a1 = *(const uint2*)(vp + 16 * s2 + 8);
;             const uint2 b0 = *(const uint2*)(vp + 32 * MV_RS + 16 * s2), b1 = *(const uint2*)(vp + 32 * MV_RS + 16 * s2 + 8);
;             u0.x = a0.x; u0.y = a0.y; u0.z = a1.x; u0.w = a1.y;
;             u1.x = b0.x; u1.y = b0.y; u1.z = b1.x; u1.w = b1.y;
;             o0 = MFMA32(__builtin_bit_cast(bf16x8, u0), pf[s2], o0);
;             o1 = MFMA32(__builtin_bit_cast(bf16x8, u1), pf[s2], o1);
;           }
.LBB0_2400:
	v_cvt_pk_bf16_f32 v122, v119, v122
	v_cvt_pk_bf16_f32 v123, v123, v124
	v_cvt_pk_bf16_f32 v124, v125, v126
	v_cvt_pk_bf16_f32 v125, v127, v128
	s_nop 0
	s_waitcnt lgkmcnt(0)
	v_mfma_f32_32x32x16_bf16 v[18:33], v[192:195], v[122:125], v[18:33]
	v_mfma_f32_32x32x16_bf16 v[2:17], v[196:199], v[122:125], v[2:17]
	v_cvt_pk_bf16_f32 v124, v40, v41
	v_cvt_pk_bf16_f32 v125, v42, v43
	v_cvt_pk_bf16_f32 v122, v34, v35
	v_cvt_pk_bf16_f32 v123, v36, v38
	v_add_f32_e32 v34, v37, v39
	v_fmac_f32_e32 v34, v118, v0
	s_nop 0
	v_mfma_f32_32x32x16_bf16 v[18:33], v[200:203], v[122:125], v[18:33]
	v_mov_b32_e32 v118, v34
	v_mfma_f32_32x32x16_bf16 v[2:17], v[204:207], v[122:125], v[2:17]
	s_cmp_ge_i32 s94, s93
	s_cbranch_scc0 .LBB0_2403

; #define MFMA32(a, b, c) __builtin_amdgcn_mfma_f32_32x32x16_bf16((a), (b), (c), 0, 0, 0)
; DI int crow(int i, int h) { return (i & 3) + 8 * (i >> 2) + 4 * h; }
; DI void mla_attention(const int wave_s, const u16* __restrict__ QC, const u16* __restrict__ KF, const u16* __restrict__ Vt, u16* __restrict__ O, char* smem) {
;     ...
;         const int ks = jt * 64 + half * 32;
;         if (ks <= q0) {
;           const u16* kp = kst + (half * 32 + r) * MK_RS + 8 * h;
;           f32x16 st = zero16();
; #pragma unroll
;           for (int s = 0; s < 6; ++s) {
;             const bf16x8 kf = *(const bf16x8*)(kp + 16 * s);
;             st = MFMA32(kf, qf[s], st);
;           }
;           if (ks == q0) {
; #pragma unroll
;             for (int i = 0; i < 16; ++i)
;               if (crow(i, h) > r) st[i] = -1e30f;
;     ...
;             const uint2 a0 = *(const uint2*)(vp + 16 * s2), a1 = *(const uint2*)(vp + 16 * s2 + 8);
;             const uint2 b0 = *(const uint2*)(vp + 32 * MV_RS + 16 * s2), b1 = *(const uint2*)(vp + 32 * MV_RS + 16 * s2 + 8);
.LBB0_2403:
	ds_read_b128 v[34:37], v120 offset:6656
	ds_read_b128 v[122:125], v120 offset:6688
	ds_read_b128 v[176:179], v120 offset:6720
	ds_read_b128 v[180:183], v120 offset:6752
	ds_read_b128 v[184:187], v120 offset:6784
	ds_read_b128 v[188:191], v120 offset:6816
	v_add_u32_e32 v209, s42, v115
	v_add_u32_e32 v208, 0x6800, v209
	v_add_u32_e32 v209, 0x7800, v209
	ds_read2_b64 v[192:195], v208 offset0:8 offset1:10
	ds_read2_b64 v[196:199], v209 offset0:40 offset1:42
	ds_read2_b64 v[200:203], v208 offset0:12 offset1:14
	ds_read2_b64 v[204:207], v209 offset0:44 offset1:46
	s_cmp_lg_u32 s81, s94
	s_waitcnt lgkmcnt(8)
	v_mfma_f32_32x32x16_bf16 v[34:49], v[34:37], v[50:53], 0
	v_mfma_f32_32x32x16_bf16 v[34:49], v[122:125], v[54:57], v[34:49]
	s_waitcnt lgkmcnt(7)
	v_mfma_f32_32x32x16_bf16 v[34:49], v[176:179], v[58:61], v[34:49]
	s_waitcnt lgkmcnt(6)
	v_mfma_f32_32x32x16_bf16 v[34:49], v[180:183], v[62:65], v[34:49]
	s_waitcnt lgkmcnt(5)
	v_mfma_f32_32x32x16_bf16 v[34:49], v[184:187], v[66:69], v[34:49]
	s_waitcnt lgkmcnt(4)
	v_mfma_f32_32x32x16_bf16 v[34:49], v[188:191], v[70:73], v[34:49]
	s_cbranch_scc1 .LBB0_2405
	s_nop 10
	v_cndmask_b32_e64 v0, v34, v245, s[6:7]
	v_cndmask_b32_e64 v35, v245, v35, s[8:9]
	v_cndmask_b32_e64 v34, v0, v34, s[8:9]
	v_cndmask_b32_e64 v36, v36, v245, s[10:11]
	v_cndmask_b32_e64 v37, v37, v245, s[12:13]
	v_cndmask_b32_e64 v38, v38, v245, s[14:15]
	v_cndmask_b32_e64 v39, v39, v245, s[16:17]
	v_cndmask_b32_e64 v40, v40, v245, s[18:19]
	v_cndmask_b32_e64 v41, v41, v245, s[20:21]
	v_cndmask_b32_e64 v42, v42, v245, s[22:23]
	v_cndmask_b32_e64 v43, v43, v245, s[24:25]
	v_cndmask_b32_e64 v44, v44, v245, s[26:27]
	v_cndmask_b32_e64 v45, v45, v245, s[28:29]
	v_cndmask_b32_e64 v46, v46, v245, s[30:31]
	v_cndmask_b32_e64 v47, v47, v245, s[34:35]
	v_cndmask_b32_e64 v48, v48, v245, s[36:37]
	v_cndmask_b32_e64 v49, v49, v245, s[38:39]

; #define MFMA32(a, b, c) __builtin_amdgcn_mfma_f32_32x32x16_bf16((a), (b), (c), 0, 0, 0)
; DI void mla_attention(const int wave_s, const u16* __restrict__ QC, const u16* __restrict__ KF, const u16* __restrict__ Vt, u16* __restrict__ O, char* smem) {
;     ...
;           bf16x8 pf[2];
; #pragma unroll
;           for (int s2 = 0; s2 < 2; ++s2) {
;             uint4 u;
;             u.x = pack2(st[8 * s2 + 0], st[8 * s2 + 1]);
;             u.y = pack2(st[8 * s2 + 2], st[8 * s2 + 3]);
;             u.z = pack2(st[8 * s2 + 4], st[8 * s2 + 5]);
;             u.w = pack2(st[8 * s2 + 6], st[8 * s2 + 7]);
;             pf[s2] = __builtin_bit_cast(bf16x8, u);
;           }
;           const u16* vp = vst + r * MV_RS + half * 32 + 4 * h;
; #pragma unroll
;           for (int s2 = 0; s2 < 2; ++s2) {
;             uint4 u0, u1;
;             const uint2 a0 = *(const uint2*)(vp + 16 * s2), a1 = *(const uint2*)(vp + 16 * s2 + 8);
;             const uint2 b0 = *(const uint2*)(vp + 32 * MV_RS + 16 * s2), b1 = *(const uint2*)(vp + 32 * MV_RS + 16 * s2 + 8);
;             u0.x = a0.x; u0.y = a0.y; u0.z = a1.x; u0.w = a1.y;
;             u1.x = b0.x; u1.y = b0.y; u1.z = b1.x; u1.w = b1.y;
;             o0 = MFMA32(__builtin_bit_cast(bf16x8, u0), pf[s2], o0);
;             o1 = MFMA32(__builtin_bit_cast(bf16x8, u1), pf[s2], o1);
;           }
.LBB0_2407:
	v_cvt_pk_bf16_f32 v120, v120, v121
	v_cvt_pk_bf16_f32 v121, v122, v123
	v_cvt_pk_bf16_f32 v122, v124, v125
	v_cvt_pk_bf16_f32 v123, v126, v127
	s_nop 0
	s_waitcnt lgkmcnt(0)
	v_mfma_f32_32x32x16_bf16 v[18:33], v[192:195], v[120:123], v[18:33]
	v_mfma_f32_32x32x16_bf16 v[2:17], v[196:199], v[120:123], v[2:17]
	v_cvt_pk_bf16_f32 v122, v40, v41
	v_cvt_pk_bf16_f32 v123, v42, v43
	v_cvt_pk_bf16_f32 v120, v34, v35
	v_cvt_pk_bf16_f32 v121, v36, v38
	v_add_f32_e32 v34, v37, v39
	v_fmac_f32_e32 v34, v118, v0
	s_nop 0
	v_mfma_f32_32x32x16_bf16 v[18:33], v[200:203], v[120:123], v[18:33]
	v_mov_b32_e32 v118, v34
	v_mfma_f32_32x32x16_bf16 v[2:17], v[204:207], v[120:123], v[2:17]
	s_andn2_b64 vcc, exec, s[74:75]
	s_mov_b64 s[42:43], -1
	s_cbranch_vccnz .LBB0_2409

; #define MFMA32(a, b, c) __builtin_amdgcn_mfma_f32_32x32x16_bf16((a), (b), (c), 0, 0, 0)
; template <class AL, class EP>
; DI void gemm2(const int wave_s, const AL al, const u16* __restrict__ Wt, const int K, const int ntm, const int ntn, const EP ep, char* smem, const u16* zrow = nullptr) {
;     ...
;         const u16* ab = al.tilebase(tm, k0);
; #pragma unroll
;         for (int q = 0; q < 4; ++q) {
;           const u16* gp = (aoff[q] == 0xffffffffu) ? (zrow + scp * 8) : (ab + aoff[q]);
;           glds16(gp, sa + q * 1024);
;         }
;       } else {
; #pragma unroll
;         for (int i = 0; i < 4; ++i) ra[i] = al.load(tm, lrow + 64 * i, k0, lcp * 8);
;       }
;       const u16* wb = wbase + k0;
; #pragma unroll
;       for (int q = 0; q < 4; ++q) glds16(wb + woff[q], sa + 32768 + q * 1024);
;     ...
;       if (more) stage_issue(kt + 1, (kt + 1) & 1);
;       __builtin_amdgcn_sched_barrier(0);
;       const char* a = smem + (kt & 1) * G_STAGE_B + wm * 128 * 128;
;       const char* b = smem + (kt & 1) * G_STAGE_B + 32768 + wn * 64 * 128;
;       if constexpr (AL::DIRECT) {
;         bf16x8 af[2][4], bfr[2][2];
; #pragma unroll
;         for (int i = 0; i < 4; ++i) af[0][i] = *(const bf16x8*)(a + i * 4096 + foff[0]);
; #pragma unroll
;         for (int j = 0; j < 2; ++j) bfr[0][j] = *(const bf16x8*)(b + j * 4096 + foff[0]);
; #pragma unroll
;         for (int s = 0; s < 4; ++s) {
;           if (s < 3) {
; #pragma unroll
;             for (int i = 0; i < 4; ++i) af[(s + 1) & 1][i] = *(const bf16x8*)(a + i * 4096 + foff[s + 1]);
; #pragma unroll
;             for (int j = 0; j < 2; ++j) bfr[(s + 1) & 1][j] = *(const bf16x8*)(b + j * 4096 + foff[s + 1]);
;           }
;           __builtin_amdgcn_sched_barrier(0);
;           __builtin_amdgcn_s_setprio(1);
; #pragma unroll
;           for (int i = 0; i < 4; ++i) {
;             acc[i][0] = MFMA32(af[s & 1][i], bfr[s & 1][0], acc[i][0]);
;             acc[i][1] = MFMA32(af[s & 1][i], bfr[s & 1][1], acc[i][1]);
;           }
;           __builtin_amdgcn_s_setprio(0);
;           __builtin_amdgcn_sched_barrier(0);
;         }
.Lrot3_loop:
	s_setprio 1
	s_waitcnt lgkmcnt(6)
	v_mfma_f32_32x32x16_bf16 v[114:129], v[186:189], v[202:205], v[114:129]
	v_mfma_f32_32x32x16_bf16 v[98:113], v[186:189], v[206:209], v[98:113]
	v_mfma_f32_32x32x16_bf16 v[82:97], v[190:193], v[202:205], v[82:97]
	v_mfma_f32_32x32x16_bf16 v[66:81], v[190:193], v[206:209], v[66:81]
	v_mfma_f32_32x32x16_bf16 v[50:65], v[194:197], v[202:205], v[50:65]
	v_mfma_f32_32x32x16_bf16 v[34:49], v[194:197], v[206:209], v[34:49]
	v_mfma_f32_32x32x16_bf16 v[18:33], v[198:201], v[202:205], v[18:33]
	v_mfma_f32_32x32x16_bf16 v[2:17], v[198:201], v[206:209], v[2:17]
	s_setprio 0
	v_add_u32_e32 v185, s10, v175
	ds_read_b128 v[186:189], v185
	ds_read_b128 v[190:193], v185 offset:4096
	ds_read_b128 v[194:197], v185 offset:8192
	ds_read_b128 v[198:201], v185 offset:12288
	v_add_u32_e32 v185, s7, v175
	ds_read_b128 v[202:205], v185 offset:32768
	ds_read_b128 v[206:209], v185 offset:36864
	s_setprio 1
	s_waitcnt lgkmcnt(6)
	v_mfma_f32_32x32x16_bf16 v[114:129], v[210:213], v[226:229], v[114:129]
	v_mfma_f32_32x32x16_bf16 v[98:113], v[210:213], v[250:253], v[98:113]
	v_mfma_f32_32x32x16_bf16 v[82:97], v[214:217], v[226:229], v[82:97]
	v_mfma_f32_32x32x16_bf16 v[66:81], v[214:217], v[250:253], v[66:81]
	v_mfma_f32_32x32x16_bf16 v[50:65], v[218:221], v[226:229], v[50:65]
	v_mfma_f32_32x32x16_bf16 v[34:49], v[218:221], v[250:253], v[34:49]
	v_mfma_f32_32x32x16_bf16 v[18:33], v[222:225], v[226:229], v[18:33]
	v_mfma_f32_32x32x16_bf16 v[2:17], v[222:225], v[250:253], v[2:17]
	s_setprio 0
	v_add_u32_e32 v185, s10, v172
	ds_read_b128 v[210:213], v185
	ds_read_b128 v[214:217], v185 offset:4096
	ds_read_b128 v[218:221], v185 offset:8192
	ds_read_b128 v[222:225], v185 offset:12288
	v_add_u32_e32 v185, s7, v172
	ds_read_b128 v[226:229], v185 offset:32768
	ds_read_b128 v[250:253], v185 offset:36864
	s_add_i32 s5, s5, 0x10000
	s_and_b32 s10, s5, 0x10000
	s_add_i32 s7, s10, s27
	s_add_i32 s10, s10, s26
	s_cmp_eq_u32 s5, 0xf0000
	s_waitcnt vmcnt(0) lgkmcnt(0)
	s_barrier
	s_cbranch_scc1 .Lrot3_tail
	s_setprio 1
	s_add_i32 m0, s5, 0x10000
	s_and_b32 m0, m0, 0x10000
	s_add_i32 m0, m0, s25
	v_mfma_f32_32x32x16_bf16 v[114:129], v[186:189], v[202:205], v[114:129]
	global_load_lds_dwordx4 v[180:181], off
	v_lshl_add_u64 v[180:181], v[180:181], 0, s[8:9]
	s_add_i32 m0, m0, 0x400
	v_mfma_f32_32x32x16_bf16 v[98:113], v[186:189], v[206:209], v[98:113]
	v_mfma_f32_32x32x16_bf16 v[82:97], v[190:193], v[202:205], v[82:97]
	global_load_lds_dwordx4 v[178:179], off
	v_lshl_add_u64 v[178:179], v[178:179], 0, s[8:9]
	s_add_i32 m0, m0, 0x400
	v_mfma_f32_32x32x16_bf16 v[66:81], v[190:193], v[206:209], v[66:81]
	v_mfma_f32_32x32x16_bf16 v[50:65], v[194:197], v[202:205], v[50:65]
	global_load_lds_dwordx4 v[176:177], off
	v_lshl_add_u64 v[176:177], v[176:177], 0, s[8:9]
	s_add_i32 m0, m0, 0x400
	v_mfma_f32_32x32x16_bf16 v[34:49], v[194:197], v[206:209], v[34:49]
	v_mfma_f32_32x32x16_bf16 v[18:33], v[198:201], v[202:205], v[18:33]
	global_load_lds_dwordx4 v[168:169], off
	v_lshl_add_u64 v[168:169], v[168:169], 0, s[8:9]
	s_add_i32 m0, m0, 0x7400
	v_mfma_f32_32x32x16_bf16 v[2:17], v[198:201], v[206:209], v[2:17]
	s_setprio 0
	v_add_u32_e32 v185, s10, v183
	ds_read_b128 v[186:189], v185
	ds_read_b128 v[190:193], v185 offset:4096
	ds_read_b128 v[194:197], v185 offset:8192
	ds_read_b128 v[198:201], v185 offset:12288
	v_add_u32_e32 v185, s7, v183
	ds_read_b128 v[202:205], v185 offset:32768
	ds_read_b128 v[206:209], v185 offset:36864
	s_setprio 1
	v_mfma_f32_32x32x16_bf16 v[114:129], v[210:213], v[226:229], v[114:129]
	global_load_lds_dwordx4 v[166:167], off
	v_lshl_add_u64 v[166:167], v[166:167], 0, s[8:9]
	s_add_i32 m0, m0, 0x400
	v_mfma_f32_32x32x16_bf16 v[98:113], v[210:213], v[250:253], v[98:113]
	v_mfma_f32_32x32x16_bf16 v[82:97], v[214:217], v[226:229], v[82:97]
	global_load_lds_dwordx4 v[164:165], off
	v_lshl_add_u64 v[164:165], v[164:165], 0, s[8:9]
	s_add_i32 m0, m0, 0x400
	v_mfma_f32_32x32x16_bf16 v[66:81], v[214:217], v[250:253], v[66:81]
	v_mfma_f32_32x32x16_bf16 v[50:65], v[218:221], v[226:229], v[50:65]
	global_load_lds_dwordx4 v[162:163], off
	v_lshl_add_u64 v[162:163], v[162:163], 0, s[8:9]
	s_add_i32 m0, m0, 0x400
	v_mfma_f32_32x32x16_bf16 v[34:49], v[218:221], v[250:253], v[34:49]
	v_mfma_f32_32x32x16_bf16 v[18:33], v[222:225], v[226:229], v[18:33]
	global_load_lds_dwordx4 v[160:161], off
	v_lshl_add_u64 v[160:161], v[160:161], 0, s[8:9]
	v_mfma_f32_32x32x16_bf16 v[2:17], v[222:225], v[250:253], v[2:17]
	s_setprio 0
	v_add_u32_e32 v185, s10, v182
	ds_read_b128 v[210:213], v185
	ds_read_b128 v[214:217], v185 offset:4096
	ds_read_b128 v[218:221], v185 offset:8192
	ds_read_b128 v[222:225], v185 offset:12288
	v_add_u32_e32 v185, s7, v182
	ds_read_b128 v[226:229], v185 offset:32768
	ds_read_b128 v[250:253], v185 offset:36864
	s_branch .Lrot3_loop

; #define MFMA32(a, b, c) __builtin_amdgcn_mfma_f32_32x32x16_bf16((a), (b), (c), 0, 0, 0)
; DI int crow(int i, int h) { return (i & 3) + 8 * (i >> 2) + 4 * h; }
; DI u16 f2bf(float a) { return (u16)(pack2(a, 0.f) & 0xffffu); }
; __global__ void __launch_bounds__(NTHR) mega(Params p) {
;     ...
;             } else if (wv < 6) {
;               const int ti = wv - 4;
;               f32x16 acc = zero16();
;               const u16* arow = ATT + (tok0 + 32 * ti + r) * 256 + hh * 64 + 8 * h;
; #pragma unroll
;               for (int s = 0; s < 4; ++s) {
;                 const bf16x8 a = *(const bf16x8*)(arow + 16 * s);
;                 const bf16x8 bv = *(const bf16x8*)(vrow + n * 64 + 16 * s);
;                 acc = MFMA32(a, bv, acc);
;               }
;               const u16* qrow = QD + (tok0 + 32 * ti + r) * 512 + hh * 128 + 8 * h;
;               const u16* ss = St + (n & 1) * 32 * 136 + r * 136 + 8 * h;
; #pragma unroll
;               for (int s = 0; s < 8; ++s) {
;                 const bf16x8 a = *(const bf16x8*)(qrow + 16 * s);
;                 const bf16x8 bs = *(const bf16x8*)(ss + 16 * s);
;                 acc = MFMA32(a, bs, acc);
;               }
; #pragma unroll
;               for (int i = 0; i < 16; ++i) O[(tok0 + 32 * ti + crow(i, h)) * 1024 + hh * 256 + dvs * 32 + r] = f2bf(acc[i]);
.LBB0_2735:
	s_mov_b64 s[10:11], -1
	s_and_b64 vcc, exec, s[6:7]
	s_cbranch_vccz .LBB0_2739
	s_andn2_b64 vcc, exec, s[8:9]
	s_cbranch_vccnz .LBB0_2738
	v_lshl_add_u64 v[18:19], s[86:87], 0, v[56:57]
	v_add_co_u32_e32 v76, vcc, 0x17800000, v18
	v_lshl_add_u64 v[22:23], s[86:87], 0, v[62:63]
	s_nop 0
	v_addc_co_u32_e32 v77, vcc, 0, v19, vcc
	v_add_co_u32_e32 v78, vcc, 0xb000000, v22
	s_and_b32 s10, s12, 32
	s_nop 0
	v_addc_co_u32_e32 v79, vcc, 0, v23, vcc
	v_lshl_add_u64 v[68:69], s[86:87], 0, v[54:55]
	s_mulk_i32 s10, 0x110
	v_add_u32_e32 v0, s10, v35
	s_mov_b32 s10, 0x13800000
	v_add_co_u32_e32 v80, vcc, s10, v68
	s_mov_b32 s10, 0x19001000
	s_nop 0
	v_addc_co_u32_e32 v81, vcc, 0, v69, vcc
	global_load_dwordx4 v[100:103], v[76:77], off
	global_load_dwordx4 v[104:107], v[78:79], off
	global_load_dwordx4 v[108:111], v[76:77], off offset:32
	global_load_dwordx4 v[112:115], v[78:79], off offset:32
	global_load_dwordx4 v[116:119], v[76:77], off offset:64
	global_load_dwordx4 v[120:123], v[78:79], off offset:64
	global_load_dwordx4 v[124:127], v[76:77], off offset:96
	global_load_dwordx4 v[128:131], v[78:79], off offset:96
	global_load_dwordx4 v[132:135], v[80:81], off
	global_load_dwordx4 v[136:139], v[80:81], off offset:32
	global_load_dwordx4 v[140:143], v[80:81], off offset:64
	global_load_dwordx4 v[144:147], v[80:81], off offset:96
	global_load_dwordx4 v[148:151], v[80:81], off offset:128
	global_load_dwordx4 v[152:155], v[80:81], off offset:160
	global_load_dwordx4 v[156:159], v[80:81], off offset:192
	global_load_dwordx4 v[160:163], v[80:81], off offset:224
	ds_read_b128 v[176:179], v0
	ds_read_b128 v[180:183], v0 offset:32
	ds_read_b128 v[184:187], v0 offset:64
	ds_read_b128 v[188:191], v0 offset:96
	ds_read_b128 v[192:195], v0 offset:128
	ds_read_b128 v[196:199], v0 offset:160
	ds_read_b128 v[200:203], v0 offset:192
	ds_read_b128 v[204:207], v0 offset:224
	s_waitcnt vmcnt(14)
	v_mfma_f32_32x32x16_bf16 v[18:33], v[100:103], v[104:107], 0
	s_waitcnt vmcnt(12)
	v_mfma_f32_32x32x16_bf16 v[18:33], v[108:111], v[112:115], v[18:33]
	s_waitcnt vmcnt(10)
	v_mfma_f32_32x32x16_bf16 v[18:33], v[116:119], v[120:123], v[18:33]
	s_waitcnt vmcnt(8)
	v_mfma_f32_32x32x16_bf16 v[18:33], v[124:127], v[128:131], v[18:33]
	s_waitcnt vmcnt(7) lgkmcnt(7)
	v_mfma_f32_32x32x16_bf16 v[18:33], v[132:135], v[176:179], v[18:33]
	s_waitcnt vmcnt(6) lgkmcnt(6)
	v_mfma_f32_32x32x16_bf16 v[18:33], v[136:139], v[180:183], v[18:33]
	s_waitcnt vmcnt(5) lgkmcnt(5)
	v_mfma_f32_32x32x16_bf16 v[18:33], v[140:143], v[184:187], v[18:33]
	s_waitcnt vmcnt(4) lgkmcnt(4)
	v_mfma_f32_32x32x16_bf16 v[18:33], v[144:147], v[188:191], v[18:33]
	s_waitcnt vmcnt(3) lgkmcnt(3)
	v_mfma_f32_32x32x16_bf16 v[18:33], v[148:151], v[192:195], v[18:33]
	s_waitcnt vmcnt(2) lgkmcnt(2)
	v_mfma_f32_32x32x16_bf16 v[18:33], v[152:155], v[196:199], v[18:33]
	s_waitcnt vmcnt(1) lgkmcnt(1)
	v_mfma_f32_32x32x16_bf16 v[18:33], v[156:159], v[200:203], v[18:33]
	s_waitcnt vmcnt(0) lgkmcnt(0)
	v_mfma_f32_32x32x16_bf16 v[18:33], v[160:163], v[204:207], v[18:33]
	v_lshl_add_u64 v[68:69], s[86:87], 0, v[58:59]
	s_nop 10
	v_cvt_pk_bf16_f32 v0, v18, s0
	global_store_short v[68:69], v0, off
	v_cvt_pk_bf16_f32 v0, v19, s0
	v_lshl_add_u64 v[18:19], s[86:87], 0, v[50:51]
	v_add_co_u32_e32 v68, vcc, s51, v18
	s_nop 1
	v_addc_co_u32_e32 v69, vcc, 0, v19, vcc
	global_store_short v[68:69], v0, off offset:2048
	v_add_co_u32_e32 v68, vcc, s10, v18
	v_cvt_pk_bf16_f32 v0, v20, s0
	s_nop 0
	v_addc_co_u32_e32 v69, vcc, 0, v19, vcc
	s_mov_b32 s10, 0x19004000
	global_store_short v[68:69], v0, off
	v_cvt_pk_bf16_f32 v0, v21, s0
	v_add_co_u32_e32 v20, vcc, s10, v18
	global_store_short v[68:69], v0, off offset:2048
	v_cvt_pk_bf16_f32 v0, v22, s0
	v_addc_co_u32_e32 v21, vcc, 0, v19, vcc
	global_store_short v[20:21], v0, off
	v_cvt_pk_bf16_f32 v0, v23, s0
	s_mov_b32 s10, 0x19005000
	global_store_short v[20:21], v0, off offset:2048
	v_add_co_u32_e32 v20, vcc, s10, v18
	v_cvt_pk_bf16_f32 v0, v24, s0
	s_nop 0
	v_addc_co_u32_e32 v21, vcc, 0, v19, vcc
	global_store_short v[20:21], v0, off
	v_cvt_pk_bf16_f32 v0, v25, s0
	s_mov_b32 s10, 0x19008000
	global_store_short v[20:21], v0, off offset:2048
	v_add_co_u32_e32 v20, vcc, s10, v18
	v_cvt_pk_bf16_f32 v0, v26, s0
	s_nop 0
	v_addc_co_u32_e32 v21, vcc, 0, v19, vcc
	global_store_short v[20:21], v0, off
	v_cvt_pk_bf16_f32 v0, v27, s0
	s_mov_b32 s10, 0x19009000
	global_store_short v[20:21], v0, off offset:2048
	v_add_co_u32_e32 v20, vcc, s10, v18
	v_cvt_pk_bf16_f32 v0, v28, s0
	s_nop 0
	v_addc_co_u32_e32 v21, vcc, 0, v19, vcc
	global_store_short v[20:21], v0, off
	v_cvt_pk_bf16_f32 v0, v29, s0
	global_store_short v[20:21], v0, off offset:2048
	v_add_co_u32_e32 v20, vcc, 0x1900c000, v18
	v_cvt_pk_bf16_f32 v0, v30, s0
	s_nop 0
	v_addc_co_u32_e32 v21, vcc, 0, v19, vcc
	global_store_short v[20:21], v0, off
	v_cvt_pk_bf16_f32 v0, v31, s0
	v_add_co_u32_e32 v18, vcc, 0x1900d000, v18
	global_store_short v[20:21], v0, off offset:2048
	v_cvt_pk_bf16_f32 v0, v32, s0
	v_addc_co_u32_e32 v19, vcc, 0, v19, vcc
	global_store_short v[18:19], v0, off
	v_cvt_pk_bf16_f32 v0, v33, s0
	global_store_short v[18:19], v0, off offset:2048

; #define MFMA32(a, b, c) __builtin_amdgcn_mfma_f32_32x32x16_bf16((a), (b), (c), 0, 0, 0)
; DI int crow(int i, int h) { return (i & 3) + 8 * (i >> 2) + 4 * h; }
; __global__ void __launch_bounds__(NTHR) mega(Params p) {
;     ...
;             if (wv < 4) {
;               const float* ex = GEX + ((size_t)(b * 128 + n) * 4 + hh) * 128 + 32 * wv;
; #pragma unroll
;               for (int i = 0; i < 16; ++i) Sacc[i] *= ex[crow(i, h)];
; #pragma unroll
;               for (int s = 0; s < 4; ++s) {
;                 const bf16x8 a = *(const bf16x8*)(kerow + n * 64 + 16 * s);
;                 const bf16x8 bv = *(const bf16x8*)(vrow + n * 64 + 16 * s);
;                 Sacc = MFMA32(a, bv, Sacc);
;               }
;               u16* sd = St + ((n + 1) & 1) * 32 * 136 + r * 136 + 32 * wv + 4 * h;
; #pragma unroll
;               for (int g = 0; g < 4; ++g) {
;                 uint2 pk;
;                 pk.x = pack2(Sacc[4 * g], Sacc[4 * g + 1]);
;                 pk.y = pack2(Sacc[4 * g + 2], Sacc[4 * g + 3]);
;                 *(uint2*)(sd + 8 * g) = pk;
;               }
.LBB0_2739:
	s_andn2_b64 vcc, exec, s[10:11]
	s_cbranch_vccnz .LBB0_2734
	v_lshl_add_u64 v[18:19], s[86:87], 0, v[52:53]
	v_add_co_u32_e32 v84, vcc, 0x18800000, v18
	s_mov_b32 s10, 0x15800000
	s_nop 0
	v_addc_co_u32_e32 v85, vcc, 0, v19, vcc
	v_lshl_add_u64 v[18:19], s[86:87], 0, v[60:61]
	v_add_co_u32_e32 v86, vcc, s10, v18
	s_mov_b32 s10, 0xb000000
	s_nop 0
	v_addc_co_u32_e32 v87, vcc, 0, v19, vcc
	v_lshl_add_u64 v[22:23], s[86:87], 0, v[62:63]
	v_add_co_u32_e32 v88, vcc, s10, v22
	s_nop 1
	v_addc_co_u32_e32 v89, vcc, 0, v23, vcc
	global_load_dwordx4 v[18:21], v[84:85], off
	global_load_dwordx4 v[22:25], v[84:85], off offset:32
	global_load_dwordx4 v[26:29], v[84:85], off offset:64
	global_load_dwordx4 v[30:33], v[84:85], off offset:96
	global_load_dwordx4 v[100:103], v[86:87], off
	global_load_dwordx4 v[104:107], v[88:89], off
	global_load_dwordx4 v[108:111], v[86:87], off offset:32
	global_load_dwordx4 v[112:115], v[88:89], off offset:32
	global_load_dwordx4 v[116:119], v[86:87], off offset:64
	global_load_dwordx4 v[120:123], v[88:89], off offset:64
	global_load_dwordx4 v[124:127], v[86:87], off offset:96
	global_load_dwordx4 v[128:131], v[88:89], off offset:96
	s_waitcnt vmcnt(8)
	v_pk_mul_f32 v[2:3], v[2:3], v[18:19]
	v_pk_mul_f32 v[4:5], v[4:5], v[20:21]
	v_pk_mul_f32 v[6:7], v[6:7], v[22:23]
	v_pk_mul_f32 v[8:9], v[8:9], v[24:25]
	v_pk_mul_f32 v[10:11], v[10:11], v[26:27]
	v_pk_mul_f32 v[12:13], v[12:13], v[28:29]
	v_pk_mul_f32 v[14:15], v[14:15], v[30:31]
	v_pk_mul_f32 v[16:17], v[16:17], v[32:33]
	s_andn2_b32 s10, 32, s12
	s_mulk_i32 s10, 0x110
	v_add_u32_e32 v0, s10, v64
	s_waitcnt vmcnt(6)
	v_mfma_f32_32x32x16_bf16 v[2:17], v[100:103], v[104:107], v[2:17]
	s_waitcnt vmcnt(4)
	v_mfma_f32_32x32x16_bf16 v[2:17], v[108:111], v[112:115], v[2:17]
	s_waitcnt vmcnt(2)
	v_mfma_f32_32x32x16_bf16 v[2:17], v[116:119], v[120:123], v[2:17]
	s_waitcnt vmcnt(0)
	v_mfma_f32_32x32x16_bf16 v[2:17], v[124:127], v[128:131], v[2:17]
	s_nop 11
	v_cvt_pk_bf16_f32 v18, v2, v3
	v_cvt_pk_bf16_f32 v19, v4, v5
	v_cvt_pk_bf16_f32 v20, v6, v7
	v_cvt_pk_bf16_f32 v21, v8, v9
	ds_write2_b64 v0, v[18:19], v[20:21] offset1:2
	v_cvt_pk_bf16_f32 v18, v10, v11
	v_cvt_pk_bf16_f32 v19, v12, v13
	v_cvt_pk_bf16_f32 v20, v14, v15
	v_cvt_pk_bf16_f32 v21, v16, v17
	ds_write2_b64 v0, v[18:19], v[20:21] offset0:4 offset1:6
	s_branch .LBB0_2734

; DI float bflo(unsigned u) { return __uint_as_float(u << 16); }
; DI float bfhi(unsigned u) { return __uint_as_float(u & 0xffff0000u); }
; DI float sigmoidf_(float x) { return __builtin_amdgcn_rcpf(1.f + __builtin_amdgcn_exp2f(-1.44269504089f * x)); }
; DI float wsum(float v) {
; #pragma unroll
;   for (int o = 32; o >= 1; o >>= 1) v += __shfl_xor(v, o);
;   return v;
; }
; __global__ void __launch_bounds__(NTHR) mega(Params p) {
;     ...
;           for (int hh = 0; hh < 4; ++hh) {
;             const uint2 ov = *(const uint2*)(O + (size_t)t * 1024 + hh * 256 + lane * 4);
;             const uint2 gv = *(const uint2*)(GO + (size_t)t * 1024 + hh * 256 + lane * 4);
;             const float o0 = bflo(ov.x), o1 = bfhi(ov.x), o2 = bflo(ov.y), o3 = bfhi(ov.y);
;             const float ss = wsum(o0 * o0 + o1 * o1 + o2 * o2 + o3 * o3);
;             const float rs = rsqrtf(ss * (1.f / 256.f) + 1e-6f);
;             const float4 gn = *(const float4*)(onorm + lane * 4);
;             const float g0 = bflo(gv.x), g1 = bfhi(gv.x), g2 = bflo(gv.y), g3 = bfhi(gv.y);
;             uint2 pk;
;             pk.x = pack2(o0 * rs * gn.x * g0 * sigmoidf_(g0), o1 * rs * gn.y * g1 * sigmoidf_(g1));
;             pk.y = pack2(o2 * rs * gn.z * g2 * sigmoidf_(g2), o3 * rs * gn.w * g3 * sigmoidf_(g3));
;             *(uint2*)(Ob + (size_t)t * 1024 + hh * 256 + lane * 4) = pk;
.LBB0_2796:
	s_ashr_i32 s5, s4, 31
	s_lshl_b64 s[6:7], s[4:5], 11
	v_lshl_add_u64 v[24:25], v[6:7], 0, s[6:7]
	flat_load_dwordx2 v[14:15], v[24:25]
	flat_load_dwordx2 v[16:17], v[24:25] offset:512
	v_lshl_add_u64 v[18:19], v[8:9], 0, s[6:7]
	flat_load_dwordx2 v[28:29], v[18:19]
	flat_load_dwordx4 v[2:5], v[10:11]
	s_mov_b32 s8, 0x358637bd
	s_add_i32 s4, s4, s54
	s_cmp_lt_i32 s4, 0x8000
	s_waitcnt vmcnt(0) lgkmcnt(0)
	v_lshlrev_b32_e32 v32, 16, v14
	v_and_b32_e32 v33, 0xffff0000, v14
	v_lshlrev_b32_e32 v20, 16, v16
	v_and_b32_e32 v21, 0xffff0000, v16
	v_lshlrev_b32_e32 v34, 16, v15
	v_and_b32_e32 v35, 0xffff0000, v15
	v_lshlrev_b32_e32 v22, 16, v17
	v_and_b32_e32 v23, 0xffff0000, v17
	v_pk_mul_f32 v[16:17], v[32:33], v[32:33]
	v_pk_mul_f32 v[30:31], v[20:21], v[20:21]
	v_pk_mul_f32 v[14:15], v[34:35], v[34:35]
	v_pk_mul_f32 v[26:27], v[22:23], v[22:23]
	v_mov_b32_e32 v36, v30
	v_mov_b32_e32 v37, v16
	v_mov_b32_e32 v16, v31
	v_mov_b32_e32 v30, v26
	v_mov_b32_e32 v31, v14
	v_pk_add_f32 v[16:17], v[36:37], v[16:17]
	v_mov_b32_e32 v14, v27
	v_pk_add_f32 v[16:17], v[16:17], v[30:31]
	v_lshlrev_b32_e32 v38, 16, v28
	v_pk_add_f32 v[14:15], v[14:15], v[16:17]
	ds_bpermute_b32 v17, v232, v15
	ds_bpermute_b32 v16, v232, v14
	v_and_b32_e32 v39, 0xffff0000, v28
	v_mul_f32_e32 v0, 0xbfb8aa3b, v38
	flat_load_dwordx2 v[26:27], v[18:19] offset:512
	v_mul_f32_e32 v40, 0xbfb8aa3b, v39
	s_waitcnt lgkmcnt(0)
	v_pk_add_f32 v[30:31], v[14:15], v[16:17]
	v_mov_b32_e32 v37, v31
	s_nop 1
	v_permlane16_swap_b32_e32 v31, v37
	v_mov_b32_e32 v36, v30
	s_nop 1
	v_permlane16_swap_b32_e32 v30, v36
	v_exp_f32_e32 v0, v0
	v_exp_f32_e32 v40, v40
	v_mov_b64_e32 v[16:17], s[8:9]
	v_lshlrev_b32_e32 v28, 16, v29
	s_waitcnt lgkmcnt(0)
	v_pk_add_f32 v[30:31], v[30:31], v[36:37]
	s_nop 1
	v_mov_b32_dpp v37, v31 row_ror:8 row_mask:0xf bank_mask:0xf
	s_nop 1
	v_mov_b32_dpp v36, v30 row_ror:8 row_mask:0xf bank_mask:0xf
	v_add_f32_e32 v0, 1.0, v0
	v_and_b32_e32 v29, 0xffff0000, v29
	v_add_f32_e32 v43, 1.0, v40
	v_rcp_f32_e32 v40, v0
	s_waitcnt lgkmcnt(0)
	v_pk_add_f32 v[30:31], v[30:31], v[36:37]
	s_nop 1
	v_mov_b32_dpp v37, v31 row_ror:4 row_mask:0xf bank_mask:0xf
	s_nop 1
	v_mov_b32_dpp v36, v30 row_ror:4 row_mask:0xf bank_mask:0xf
	v_mul_f32_e32 v41, 0xbfb8aa3b, v28
	v_mul_f32_e32 v42, 0xbfb8aa3b, v29
	v_exp_f32_e32 v41, v41
	v_exp_f32_e32 v42, v42
	s_waitcnt lgkmcnt(0)
	v_pk_add_f32 v[30:31], v[30:31], v[36:37]
	s_nop 1
	v_mov_b32_dpp v37, v31 row_ror:2 row_mask:0xf bank_mask:0xf
	s_nop 1
	v_mov_b32_dpp v36, v30 row_ror:2 row_mask:0xf bank_mask:0xf
	v_add_f32_e32 v44, 1.0, v41
	v_add_f32_e32 v42, 1.0, v42
	v_rcp_f32_e32 v41, v43
	v_lshl_add_u64 v[14:15], v[12:13], 0, s[6:7]
	s_waitcnt lgkmcnt(0)
	v_pk_add_f32 v[30:31], v[30:31], v[36:37]
	s_nop 1
	v_mov_b32_dpp v37, v31 row_ror:1 row_mask:0xf bank_mask:0xf
	s_nop 1
	v_mov_b32_dpp v36, v30 row_ror:1 row_mask:0xf bank_mask:0xf
	s_waitcnt lgkmcnt(0)
	v_pk_add_f32 v[30:31], v[30:31], v[36:37]
	s_nop 0
	v_pk_fma_f32 v[30:31], v[30:31], s[10:11], v[16:17] op_sel_hi:[1,0,0]
	v_rcp_f32_e32 v36, v44
	v_mul_f32_e32 v0, 0x4b800000, v31
	v_cmp_gt_f32_e32 vcc, s9, v31
	v_rcp_f32_e32 v37, v42
	s_nop 0
	v_cndmask_b32_e32 v0, v31, v0, vcc
	v_rsq_f32_e32 v0, v0
	s_nop 0
	v_mul_f32_e32 v31, 0x45800000, v0
	v_cndmask_b32_e32 v0, v0, v31, vcc
	v_pk_mul_f32 v[32:33], v[0:1], v[32:33] op_sel_hi:[0,1]
	v_pk_mul_f32 v[34:35], v[0:1], v[34:35] op_sel_hi:[0,1]
	v_pk_mul_f32 v[2:3], v[2:3], v[32:33]
	v_pk_mul_f32 v[4:5], v[4:5], v[34:35]
	v_pk_mul_f32 v[2:3], v[2:3], v[38:39]
	v_pk_mul_f32 v[4:5], v[4:5], v[28:29]
	v_pk_mul_f32 v[2:3], v[40:41], v[2:3]
	v_pk_mul_f32 v[4:5], v[36:37], v[4:5]
	v_cvt_pk_bf16_f32 v2, v2, v3
	v_cvt_pk_bf16_f32 v3, v4, v5
	flat_store_dwordx2 v[14:15], v[2:3]
	flat_load_dwordx4 v[2:5], v[10:11]
	s_nop 0
	flat_load_dwordx2 v[32:33], v[24:25] offset:1024
	flat_load_dwordx2 v[34:35], v[24:25] offset:1536
	flat_load_dwordx2 v[28:29], v[18:19] offset:1024
	v_cmp_gt_f32_e32 vcc, s9, v30
	flat_load_dwordx2 v[18:19], v[18:19] offset:1536
	s_waitcnt vmcnt(0)
	v_lshlrev_b32_e32 v24, 16, v26
	v_and_b32_e32 v25, 0xffff0000, v26
	v_lshlrev_b32_e32 v26, 16, v27
	v_mul_f32_e32 v0, 0xbfb8aa3b, v24
	v_mul_f32_e32 v36, 0xbfb8aa3b, v26
	v_exp_f32_e32 v0, v0
	v_exp_f32_e32 v36, v36
	v_and_b32_e32 v27, 0xffff0000, v27
	v_mul_f32_e32 v31, 0xbfb8aa3b, v25
	v_add_f32_e32 v0, 1.0, v0
	v_add_f32_e32 v38, 1.0, v36
	v_rcp_f32_e32 v36, v0
	v_mul_f32_e32 v0, 0x4b800000, v30
	v_mul_f32_e32 v37, 0xbfb8aa3b, v27
	v_cndmask_b32_e32 v0, v30, v0, vcc
	v_exp_f32_e32 v31, v31
	v_exp_f32_e32 v37, v37
	v_rsq_f32_e32 v0, v0
	v_rcp_f32_e32 v30, v38
	v_add_f32_e32 v31, 1.0, v31
	v_add_f32_e32 v39, 1.0, v37
	v_mul_f32_e32 v38, 0x45800000, v0
	v_rcp_f32_e32 v37, v31
	v_rcp_f32_e32 v31, v39
	v_cndmask_b32_e32 v0, v0, v38, vcc
	v_pk_mul_f32 v[20:21], v[0:1], v[20:21] op_sel_hi:[0,1]
	v_pk_mul_f32 v[22:23], v[0:1], v[22:23] op_sel_hi:[0,1]
	s_waitcnt lgkmcnt(0)
; DI float bflo(unsigned u) { return __uint_as_float(u << 16); }
; DI float bfhi(unsigned u) { return __uint_as_float(u & 0xffff0000u); }
; DI float sigmoidf_(float x) { return __builtin_amdgcn_rcpf(1.f + __builtin_amdgcn_exp2f(-1.44269504089f * x)); }
; DI float wsum(float v) {
; #pragma unroll
;   for (int o = 32; o >= 1; o >>= 1) v += __shfl_xor(v, o);
;   return v;
; }
; __global__ void __launch_bounds__(NTHR) mega(Params p) {
;     ...
;           for (int hh = 0; hh < 4; ++hh) {
;             const uint2 ov = *(const uint2*)(O + (size_t)t * 1024 + hh * 256 + lane * 4);
;             const uint2 gv = *(const uint2*)(GO + (size_t)t * 1024 + hh * 256 + lane * 4);
;             const float o0 = bflo(ov.x), o1 = bfhi(ov.x), o2 = bflo(ov.y), o3 = bfhi(ov.y);
;             const float ss = wsum(o0 * o0 + o1 * o1 + o2 * o2 + o3 * o3);
;             const float rs = rsqrtf(ss * (1.f / 256.f) + 1e-6f);
;             const float4 gn = *(const float4*)(onorm + lane * 4);
;             const float g0 = bflo(gv.x), g1 = bfhi(gv.x), g2 = bflo(gv.y), g3 = bfhi(gv.y);
;             uint2 pk;
;             pk.x = pack2(o0 * rs * gn.x * g0 * sigmoidf_(g0), o1 * rs * gn.y * g1 * sigmoidf_(g1));
;             pk.y = pack2(o2 * rs * gn.z * g2 * sigmoidf_(g2), o3 * rs * gn.w * g3 * sigmoidf_(g3));
;             *(uint2*)(Ob + (size_t)t * 1024 + hh * 256 + lane * 4) = pk;
	v_pk_mul_f32 v[2:3], v[2:3], v[20:21]
	v_pk_mul_f32 v[4:5], v[4:5], v[22:23]
	v_pk_mul_f32 v[2:3], v[2:3], v[24:25]
	v_pk_mul_f32 v[4:5], v[4:5], v[26:27]
	v_pk_mul_f32 v[2:3], v[36:37], v[2:3]
	v_pk_mul_f32 v[4:5], v[30:31], v[4:5]
	v_cvt_pk_bf16_f32 v2, v2, v3
	v_cvt_pk_bf16_f32 v3, v4, v5
	flat_store_dwordx2 v[14:15], v[2:3] offset:512
	flat_load_dwordx4 v[2:5], v[10:11]
	v_lshlrev_b32_e32 v26, 16, v32
	v_and_b32_e32 v27, 0xffff0000, v32
	v_lshlrev_b32_e32 v20, 16, v34
	v_and_b32_e32 v21, 0xffff0000, v34
	v_lshlrev_b32_e32 v24, 16, v33
	v_and_b32_e32 v25, 0xffff0000, v33
	v_lshlrev_b32_e32 v22, 16, v35
	v_and_b32_e32 v23, 0xffff0000, v35
	v_pk_mul_f32 v[32:33], v[26:27], v[26:27]
	v_pk_mul_f32 v[36:37], v[20:21], v[20:21]
	v_pk_mul_f32 v[30:31], v[24:25], v[24:25]
	v_pk_mul_f32 v[34:35], v[22:23], v[22:23]
	v_mov_b32_e32 v38, v36
	v_mov_b32_e32 v39, v32
	v_mov_b32_e32 v32, v37
	v_mov_b32_e32 v36, v34
	v_mov_b32_e32 v37, v30
	v_pk_add_f32 v[32:33], v[38:39], v[32:33]
	v_mov_b32_e32 v30, v35
	v_pk_add_f32 v[32:33], v[32:33], v[36:37]
	v_lshlrev_b32_e32 v34, 16, v28
	v_pk_add_f32 v[30:31], v[30:31], v[32:33]
	v_mov_b32_e32 v33, v31
	s_nop 1
	v_permlane32_swap_b32_e32 v31, v33
	v_mov_b32_e32 v32, v30
	s_nop 1
	v_permlane32_swap_b32_e32 v30, v32
	v_and_b32_e32 v35, 0xffff0000, v28
	v_mul_f32_e32 v0, 0xbfb8aa3b, v34
	v_mul_f32_e32 v36, 0xbfb8aa3b, v35
	v_exp_f32_e32 v0, v0
	s_waitcnt lgkmcnt(0)
	v_pk_add_f32 v[30:31], v[30:31], v[32:33]
	v_mov_b32_e32 v33, v31
	s_nop 1
	v_permlane16_swap_b32_e32 v31, v33
	v_mov_b32_e32 v32, v30
	s_nop 1
	v_permlane16_swap_b32_e32 v30, v32
	v_exp_f32_e32 v36, v36
	v_add_f32_e32 v0, 1.0, v0
	v_lshlrev_b32_e32 v28, 16, v29
	v_and_b32_e32 v29, 0xffff0000, v29
	s_waitcnt lgkmcnt(0)
	v_pk_add_f32 v[30:31], v[30:31], v[32:33]
	s_nop 1
	v_mov_b32_dpp v33, v31 row_ror:8 row_mask:0xf bank_mask:0xf
	s_nop 1
	v_mov_b32_dpp v32, v30 row_ror:8 row_mask:0xf bank_mask:0xf
	v_add_f32_e32 v39, 1.0, v36
	v_rcp_f32_e32 v36, v0
	v_mul_f32_e32 v37, 0xbfb8aa3b, v28
	v_mul_f32_e32 v38, 0xbfb8aa3b, v29
	s_waitcnt lgkmcnt(0)
	v_pk_add_f32 v[30:31], v[30:31], v[32:33]
	s_nop 1
	v_mov_b32_dpp v33, v31 row_ror:4 row_mask:0xf bank_mask:0xf
	s_nop 1
	v_mov_b32_dpp v32, v30 row_ror:4 row_mask:0xf bank_mask:0xf
	v_exp_f32_e32 v37, v37
	v_exp_f32_e32 v38, v38
	s_waitcnt lgkmcnt(0)
	v_pk_add_f32 v[30:31], v[30:31], v[32:33]
	s_nop 1
	v_mov_b32_dpp v33, v31 row_ror:2 row_mask:0xf bank_mask:0xf
	s_nop 1
	v_mov_b32_dpp v32, v30 row_ror:2 row_mask:0xf bank_mask:0xf
	v_add_f32_e32 v40, 1.0, v37
	v_add_f32_e32 v38, 1.0, v38
	v_rcp_f32_e32 v37, v39
	s_waitcnt lgkmcnt(0)
	v_pk_add_f32 v[30:31], v[30:31], v[32:33]
	s_nop 1
	v_mov_b32_dpp v33, v31 row_ror:1 row_mask:0xf bank_mask:0xf
	s_nop 1
	v_mov_b32_dpp v32, v30 row_ror:1 row_mask:0xf bank_mask:0xf
	s_waitcnt lgkmcnt(0)
	v_pk_add_f32 v[30:31], v[30:31], v[32:33]
	s_nop 0
	v_pk_fma_f32 v[16:17], v[30:31], s[10:11], v[16:17] op_sel_hi:[1,0,0]
	v_rcp_f32_e32 v30, v40
	v_mul_f32_e32 v0, 0x4b800000, v17
	v_cmp_gt_f32_e32 vcc, s9, v17
	v_rcp_f32_e32 v31, v38
	s_nop 0
	v_cndmask_b32_e32 v0, v17, v0, vcc
	v_rsq_f32_e32 v0, v0
	s_nop 0
	v_mul_f32_e32 v17, 0x45800000, v0
	v_cndmask_b32_e32 v0, v0, v17, vcc
	v_pk_mul_f32 v[26:27], v[0:1], v[26:27] op_sel_hi:[0,1]
	v_pk_mul_f32 v[24:25], v[0:1], v[24:25] op_sel_hi:[0,1]
	s_waitcnt vmcnt(0)
	v_pk_mul_f32 v[2:3], v[2:3], v[26:27]
	v_pk_mul_f32 v[4:5], v[4:5], v[24:25]
	v_pk_mul_f32 v[2:3], v[2:3], v[34:35]
	v_pk_mul_f32 v[4:5], v[4:5], v[28:29]
	v_pk_mul_f32 v[2:3], v[36:37], v[2:3]
	v_pk_mul_f32 v[4:5], v[30:31], v[4:5]
	v_cvt_pk_bf16_f32 v2, v2, v3
	v_cvt_pk_bf16_f32 v3, v4, v5
	flat_store_dwordx2 v[14:15], v[2:3] offset:1024
	flat_load_dwordx4 v[2:5], v[10:11]
	v_lshlrev_b32_e32 v24, 16, v18
	v_and_b32_e32 v25, 0xffff0000, v18
	v_lshlrev_b32_e32 v18, 16, v19
	v_mul_f32_e32 v0, 0xbfb8aa3b, v24
	v_mul_f32_e32 v26, 0xbfb8aa3b, v18
	v_exp_f32_e32 v0, v0
	v_exp_f32_e32 v26, v26
	v_and_b32_e32 v19, 0xffff0000, v19
	v_cmp_gt_f32_e32 vcc, s9, v16
	v_add_f32_e32 v0, 1.0, v0
	v_add_f32_e32 v28, 1.0, v26
	v_rcp_f32_e32 v26, v0
	v_mul_f32_e32 v0, 0x4b800000, v16
	v_mul_f32_e32 v17, 0xbfb8aa3b, v25
	v_mul_f32_e32 v27, 0xbfb8aa3b, v19
	v_cndmask_b32_e32 v0, v16, v0, vcc
	v_exp_f32_e32 v17, v17
	v_exp_f32_e32 v27, v27
	v_rsq_f32_e32 v0, v0
	v_rcp_f32_e32 v16, v28
	v_add_f32_e32 v17, 1.0, v17
	v_add_f32_e32 v29, 1.0, v27
	v_mul_f32_e32 v28, 0x45800000, v0
	v_rcp_f32_e32 v27, v17
	v_rcp_f32_e32 v17, v29
	v_cndmask_b32_e32 v0, v0, v28, vcc
	v_pk_mul_f32 v[20:21], v[0:1], v[20:21] op_sel_hi:[0,1]
	v_pk_mul_f32 v[22:23], v[0:1], v[22:23] op_sel_hi:[0,1]
	s_waitcnt vmcnt(0) lgkmcnt(0)
	v_pk_mul_f32 v[2:3], v[2:3], v[20:21]
	v_pk_mul_f32 v[4:5], v[4:5], v[22:23]
	v_pk_mul_f32 v[2:3], v[2:3], v[24:25]
	v_pk_mul_f32 v[4:5], v[4:5], v[18:19]
	v_pk_mul_f32 v[2:3], v[26:27], v[2:3]
	v_pk_mul_f32 v[4:5], v[16:17], v[4:5]
	v_cvt_pk_bf16_f32 v2, v2, v3
	v_cvt_pk_bf16_f32 v3, v4, v5
	flat_store_dwordx2 v[14:15], v[2:3] offset:1536
	s_cbranch_scc1 .LBB0_2796
	s_mov_b32 s33, 0x800000

; #define MFMA32(a, b, c) __builtin_amdgcn_mfma_f32_32x32x16_bf16((a), (b), (c), 0, 0, 0)
; template <class AL, class EP>
; DI void gemm2(const int wave_s, const AL al, const u16* __restrict__ Wt, const int K, const int ntm, const int ntn, const EP ep, char* smem, const u16* zrow = nullptr) {
;     ...
;         const u16* ab = al.tilebase(tm, k0);
; #pragma unroll
;         for (int q = 0; q < 4; ++q) {
;           const u16* gp = (aoff[q] == 0xffffffffu) ? (zrow + scp * 8) : (ab + aoff[q]);
;           glds16(gp, sa + q * 1024);
;         }
;       } else {
; #pragma unroll
;         for (int i = 0; i < 4; ++i) ra[i] = al.load(tm, lrow + 64 * i, k0, lcp * 8);
;       }
;       const u16* wb = wbase + k0;
; #pragma unroll
;       for (int q = 0; q < 4; ++q) glds16(wb + woff[q], sa + 32768 + q * 1024);
;     ...
;       if (more) stage_issue(kt + 1, (kt + 1) & 1);
;       __builtin_amdgcn_sched_barrier(0);
;       const char* a = smem + (kt & 1) * G_STAGE_B + wm * 128 * 128;
;       const char* b = smem + (kt & 1) * G_STAGE_B + 32768 + wn * 64 * 128;
;       if constexpr (AL::DIRECT) {
;         bf16x8 af[2][4], bfr[2][2];
; #pragma unroll
;         for (int i = 0; i < 4; ++i) af[0][i] = *(const bf16x8*)(a + i * 4096 + foff[0]);
; #pragma unroll
;         for (int j = 0; j < 2; ++j) bfr[0][j] = *(const bf16x8*)(b + j * 4096 + foff[0]);
; #pragma unroll
;         for (int s = 0; s < 4; ++s) {
;           if (s < 3) {
; #pragma unroll
;             for (int i = 0; i < 4; ++i) af[(s + 1) & 1][i] = *(const bf16x8*)(a + i * 4096 + foff[s + 1]);
; #pragma unroll
;             for (int j = 0; j < 2; ++j) bfr[(s + 1) & 1][j] = *(const bf16x8*)(b + j * 4096 + foff[s + 1]);
;           }
;           __builtin_amdgcn_sched_barrier(0);
;           __builtin_amdgcn_s_setprio(1);
; #pragma unroll
;           for (int i = 0; i < 4; ++i) {
;             acc[i][0] = MFMA32(af[s & 1][i], bfr[s & 1][0], acc[i][0]);
;             acc[i][1] = MFMA32(af[s & 1][i], bfr[s & 1][1], acc[i][1]);
;           }
;           __builtin_amdgcn_s_setprio(0);
;           __builtin_amdgcn_sched_barrier(0);
;         }
.Lrot5_loop:
	s_setprio 1
	s_waitcnt lgkmcnt(6)
	v_mfma_f32_32x32x16_bf16 v[114:129], v[186:189], v[202:205], v[114:129]
	v_mfma_f32_32x32x16_bf16 v[98:113], v[186:189], v[206:209], v[98:113]
	v_mfma_f32_32x32x16_bf16 v[82:97], v[190:193], v[202:205], v[82:97]
	v_mfma_f32_32x32x16_bf16 v[66:81], v[190:193], v[206:209], v[66:81]
	v_mfma_f32_32x32x16_bf16 v[50:65], v[194:197], v[202:205], v[50:65]
	v_mfma_f32_32x32x16_bf16 v[34:49], v[194:197], v[206:209], v[34:49]
	v_mfma_f32_32x32x16_bf16 v[18:33], v[198:201], v[202:205], v[18:33]
	v_mfma_f32_32x32x16_bf16 v[2:17], v[198:201], v[206:209], v[2:17]
	s_setprio 0
	v_add_u32_e32 v0, s14, v175
	ds_read_b128 v[186:189], v0
	ds_read_b128 v[190:193], v0 offset:4096
	ds_read_b128 v[194:197], v0 offset:8192
	ds_read_b128 v[198:201], v0 offset:12288
	v_add_u32_e32 v0, s11, v175
	ds_read_b128 v[202:205], v0 offset:32768
	ds_read_b128 v[206:209], v0 offset:36864
	s_setprio 1
	s_waitcnt lgkmcnt(6)
	v_mfma_f32_32x32x16_bf16 v[114:129], v[210:213], v[226:229], v[114:129]
	v_mfma_f32_32x32x16_bf16 v[98:113], v[210:213], v[250:253], v[98:113]
	v_mfma_f32_32x32x16_bf16 v[82:97], v[214:217], v[226:229], v[82:97]
	v_mfma_f32_32x32x16_bf16 v[66:81], v[214:217], v[250:253], v[66:81]
	v_mfma_f32_32x32x16_bf16 v[50:65], v[218:221], v[226:229], v[50:65]
	v_mfma_f32_32x32x16_bf16 v[34:49], v[218:221], v[250:253], v[34:49]
	v_mfma_f32_32x32x16_bf16 v[18:33], v[222:225], v[226:229], v[18:33]
	v_mfma_f32_32x32x16_bf16 v[2:17], v[222:225], v[250:253], v[2:17]
	s_setprio 0
	v_add_u32_e32 v0, s14, v172
	ds_read_b128 v[210:213], v0
	ds_read_b128 v[214:217], v0 offset:4096
	ds_read_b128 v[218:221], v0 offset:8192
	ds_read_b128 v[222:225], v0 offset:12288
	v_add_u32_e32 v0, s11, v172
	ds_read_b128 v[226:229], v0 offset:32768
	ds_read_b128 v[250:253], v0 offset:36864
	s_add_i32 s9, s9, 0x10000
	s_and_b32 s14, s9, 0x10000
	s_add_i32 s11, s14, s29
	s_add_i32 s14, s14, s28
	s_cmp_eq_u32 s9, 0xf0000
	s_waitcnt vmcnt(0) lgkmcnt(0)
	s_barrier
	s_cbranch_scc1 .Lrot5_tail
	s_setprio 1
	s_add_i32 m0, s9, 0x10000
	s_and_b32 m0, m0, 0x10000
	s_add_i32 m0, m0, s27
	v_mfma_f32_32x32x16_bf16 v[114:129], v[186:189], v[202:205], v[114:129]
	global_load_lds_dwordx4 v[180:181], off
	v_lshl_add_u64 v[180:181], v[180:181], 0, s[12:13]
	s_add_i32 m0, m0, 0x400
	v_mfma_f32_32x32x16_bf16 v[98:113], v[186:189], v[206:209], v[98:113]
	v_mfma_f32_32x32x16_bf16 v[82:97], v[190:193], v[202:205], v[82:97]
	global_load_lds_dwordx4 v[178:179], off
	v_lshl_add_u64 v[178:179], v[178:179], 0, s[12:13]
	s_add_i32 m0, m0, 0x400
	v_mfma_f32_32x32x16_bf16 v[66:81], v[190:193], v[206:209], v[66:81]
	v_mfma_f32_32x32x16_bf16 v[50:65], v[194:197], v[202:205], v[50:65]
	global_load_lds_dwordx4 v[176:177], off
	v_lshl_add_u64 v[176:177], v[176:177], 0, s[12:13]
	s_add_i32 m0, m0, 0x400
	v_mfma_f32_32x32x16_bf16 v[34:49], v[194:197], v[206:209], v[34:49]
	v_mfma_f32_32x32x16_bf16 v[18:33], v[198:201], v[202:205], v[18:33]
	global_load_lds_dwordx4 v[168:169], off
	v_lshl_add_u64 v[168:169], v[168:169], 0, s[12:13]
	s_add_i32 m0, m0, 0x7400
	v_mfma_f32_32x32x16_bf16 v[2:17], v[198:201], v[206:209], v[2:17]
	s_setprio 0
	v_add_u32_e32 v0, s14, v183
	ds_read_b128 v[186:189], v0
	ds_read_b128 v[190:193], v0 offset:4096
	ds_read_b128 v[194:197], v0 offset:8192
	ds_read_b128 v[198:201], v0 offset:12288
	v_add_u32_e32 v0, s11, v183
	ds_read_b128 v[202:205], v0 offset:32768
	ds_read_b128 v[206:209], v0 offset:36864
	s_setprio 1
	v_mfma_f32_32x32x16_bf16 v[114:129], v[210:213], v[226:229], v[114:129]
	global_load_lds_dwordx4 v[166:167], off
	v_lshl_add_u64 v[166:167], v[166:167], 0, s[12:13]
	s_add_i32 m0, m0, 0x400
	v_mfma_f32_32x32x16_bf16 v[98:113], v[210:213], v[250:253], v[98:113]
	v_mfma_f32_32x32x16_bf16 v[82:97], v[214:217], v[226:229], v[82:97]
	global_load_lds_dwordx4 v[164:165], off
	v_lshl_add_u64 v[164:165], v[164:165], 0, s[12:13]
	s_add_i32 m0, m0, 0x400
	v_mfma_f32_32x32x16_bf16 v[66:81], v[214:217], v[250:253], v[66:81]
	v_mfma_f32_32x32x16_bf16 v[50:65], v[218:221], v[226:229], v[50:65]
	global_load_lds_dwordx4 v[162:163], off
	v_lshl_add_u64 v[162:163], v[162:163], 0, s[12:13]
	s_add_i32 m0, m0, 0x400
	v_mfma_f32_32x32x16_bf16 v[34:49], v[218:221], v[250:253], v[34:49]
	v_mfma_f32_32x32x16_bf16 v[18:33], v[222:225], v[226:229], v[18:33]
	global_load_lds_dwordx4 v[160:161], off
	v_lshl_add_u64 v[160:161], v[160:161], 0, s[12:13]
	v_mfma_f32_32x32x16_bf16 v[2:17], v[222:225], v[250:253], v[2:17]
	s_setprio 0
	v_add_u32_e32 v0, s14, v182
	ds_read_b128 v[210:213], v0
	ds_read_b128 v[214:217], v0 offset:4096
	ds_read_b128 v[218:221], v0 offset:8192
	ds_read_b128 v[222:225], v0 offset:12288
	v_add_u32_e32 v0, s11, v182
	ds_read_b128 v[226:229], v0 offset:32768
	ds_read_b128 v[250:253], v0 offset:36864
	s_branch .Lrot5_loop

; DI float bflo(unsigned u) { return __uint_as_float(u << 16); }
; DI float bfhi(unsigned u) { return __uint_as_float(u & 0xffff0000u); }
; DI void rowpass(const int wave_s, const float* __restrict__ xin, u16* __restrict__ X, const u16* __restrict__ Y, const float* __restrict__ gpost,
;                 const float* __restrict__ gpre, u16* __restrict__ HN, float* __restrict__ outf) {
;     ...
;     if (Y) {
;       float4 y[4];
;       float ss = 0.f;
; #pragma unroll
;       for (int j = 0; j < 4; ++j) {
;         const uint2 yu = *(const uint2*)(Y + (size_t)row * 1024 + j * 256 + lane * 4);
;         y[j] = make_float4(bflo(yu.x), bfhi(yu.x), bflo(yu.y), bfhi(yu.y));
;         ss += y[j].x * y[j].x + y[j].y * y[j].y + y[j].z * y[j].z + y[j].w * y[j].w;
;       }
;       ss = wsum(ss);
;       const float rs = rsqrtf(ss * (1.f / 1024.f) + 1e-6f);
; #pragma unroll
;       for (int j = 0; j < 4; ++j) {
;         const float4 g = *(const float4*)(gpost + j * 256 + lane * 4);
;         const uint2 xu = *(const uint2*)(X + (size_t)row * 1024 + j * 256 + lane * 4);
;         x[j] = make_float4(bflo(xu.x), bfhi(xu.x), bflo(xu.y), bfhi(xu.y));
;         x[j].x += y[j].x * rs * g.x; x[j].y += y[j].y * rs * g.y; x[j].z += y[j].z * rs * g.z; x[j].w += y[j].w * rs * g.w;
;       }
;     } else {
; #pragma unroll
;       for (int j = 0; j < 4; ++j) x[j] = *(const float4*)(xin + (size_t)row * 1024 + j * 256 + lane * 4);
;     }
;     float ss2 = 0.f;
; #pragma unroll
;     for (int j = 0; j < 4; ++j) {
;       if (outf) *(float4*)(outf + (size_t)row * 1024 + j * 256 + lane * 4) = x[j];
;       else { uint2 xp; xp.x = pack2(x[j].x, x[j].y); xp.y = pack2(x[j].z, x[j].w); *(uint2*)(X + (size_t)row * 1024 + j * 256 + lane * 4) = xp; }
;       ss2 += x[j].x * x[j].x + x[j].y * x[j].y + x[j].z * x[j].z + x[j].w * x[j].w;
.LBB0_3261:
	s_ashr_i32 s7, s6, 31
	s_lshl_b64 s[14:15], s[6:7], 11
	v_lshl_add_u64 v[26:27], v[18:19], 0, s[14:15]
	flat_load_dwordx2 v[28:29], v[26:27]
	flat_load_dwordx2 v[30:31], v[26:27] offset:512
	flat_load_dwordx2 v[32:33], v[26:27] offset:1024
	s_nop 0
	flat_load_dwordx2 v[26:27], v[26:27] offset:1536
	v_lshl_add_u64 v[44:45], v[20:21], 0, s[14:15]
	flat_load_dwordx2 v[34:35], v[44:45]
	flat_load_dwordx2 v[36:37], v[44:45] offset:512
	flat_load_dwordx2 v[38:39], v[44:45] offset:1024
	flat_load_dwordx2 v[40:41], v[44:45] offset:1536
	s_andn2_b64 vcc, exec, s[8:9]
	s_waitcnt vmcnt(0) lgkmcnt(0)
	v_and_b32_e32 v43, 0xffff0000, v28
	v_and_b32_e32 v47, 0xffff0000, v30
	v_lshlrev_b32_e32 v42, 16, v28
	v_lshlrev_b32_e32 v46, 16, v30
	v_and_b32_e32 v49, 0xffff0000, v32
	v_and_b32_e32 v51, 0xffff0000, v26
	v_mov_b32_e32 v58, v43
	v_mov_b32_e32 v59, v47
	v_lshlrev_b32_e32 v28, 16, v29
	v_lshlrev_b32_e32 v30, 16, v31
	v_lshlrev_b32_e32 v48, 16, v32
	v_lshlrev_b32_e32 v50, 16, v26
	v_mov_b32_e32 v56, v42
	v_mov_b32_e32 v57, v46
	v_mov_b32_e32 v66, v49
	v_mov_b32_e32 v67, v51
	v_pk_mul_f32 v[58:59], v[58:59], v[58:59]
	v_and_b32_e32 v29, 0xffff0000, v29
	v_and_b32_e32 v31, 0xffff0000, v31
	v_lshlrev_b32_e32 v32, 16, v33
	v_lshlrev_b32_e32 v26, 16, v27
	v_mov_b32_e32 v52, v28
	v_mov_b32_e32 v53, v30
	v_mov_b32_e32 v64, v48
	v_mov_b32_e32 v65, v50
	v_pk_mul_f32 v[66:67], v[66:67], v[66:67]
	v_pk_fma_f32 v[56:57], v[56:57], v[56:57], v[58:59]
	v_and_b32_e32 v33, 0xffff0000, v33
	v_and_b32_e32 v27, 0xffff0000, v27
	v_mov_b32_e32 v54, v29
	v_mov_b32_e32 v55, v31
	v_mov_b32_e32 v60, v32
	v_mov_b32_e32 v61, v26
	v_pk_fma_f32 v[58:59], v[64:65], v[64:65], v[66:67]
	v_pk_fma_f32 v[52:53], v[52:53], v[52:53], v[56:57]
	v_mov_b32_e32 v62, v33
	v_mov_b32_e32 v63, v27
	v_pk_fma_f32 v[56:57], v[60:61], v[60:61], v[58:59]
	v_pk_fma_f32 v[52:53], v[54:55], v[54:55], v[52:53]
	v_pk_fma_f32 v[54:55], v[62:63], v[62:63], v[56:57]
	v_add_f32_e32 v0, v52, v53
	v_add_f32_e32 v0, v0, v54
	v_add_f32_e32 v0, v0, v55
	v_mov_b32_e32 v52, v0
	s_nop 1
	v_permlane32_swap_b32_e32 v0, v52
	v_lshlrev_b32_e32 v56, 16, v38
	v_lshlrev_b32_e32 v58, 16, v39
	v_and_b32_e32 v59, 0xffff0000, v39
	v_lshlrev_b32_e32 v54, 16, v36
	s_waitcnt lgkmcnt(0)
	v_add_f32_e32 v0, v0, v52
	v_mov_b32_e32 v52, v0
	s_nop 1
	v_permlane16_swap_b32_e32 v0, v52
	v_lshlrev_b32_e32 v60, 16, v40
	v_lshlrev_b32_e32 v62, 16, v41
	v_and_b32_e32 v63, 0xffff0000, v41
	s_waitcnt lgkmcnt(0)
	v_add_f32_e32 v0, v0, v52
	s_nop 1
	v_mov_b32_dpp v53, v0 row_ror:8 row_mask:0xf bank_mask:0xf
	v_lshlrev_b32_e32 v52, 16, v34
	s_waitcnt lgkmcnt(0)
	v_add_f32_e32 v0, v0, v53
	s_nop 1
	v_mov_b32_dpp v55, v0 row_ror:4 row_mask:0xf bank_mask:0xf
	v_and_b32_e32 v53, 0xffff0000, v34
	v_lshlrev_b32_e32 v34, 16, v35
	v_and_b32_e32 v35, 0xffff0000, v35
	s_waitcnt lgkmcnt(0)
	v_add_f32_e32 v0, v0, v55
	s_nop 1
	v_mov_b32_dpp v57, v0 row_ror:2 row_mask:0xf bank_mask:0xf
	v_and_b32_e32 v55, 0xffff0000, v36
	v_lshlrev_b32_e32 v36, 16, v37
	v_and_b32_e32 v37, 0xffff0000, v37
	s_waitcnt lgkmcnt(0)
	v_add_f32_e32 v0, v0, v57
	s_nop 1
	v_mov_b32_dpp v61, v0 row_ror:1 row_mask:0xf bank_mask:0xf
	v_and_b32_e32 v57, 0xffff0000, v38
	s_waitcnt lgkmcnt(0)
	v_add_f32_e32 v0, v0, v61
	v_fmamk_f32 v0, v0, 0x3a800000, v170
	v_mul_f32_e32 v38, 0x4b800000, v0
	v_cmp_gt_f32_e64 s[4:5], s16, v0
	v_and_b32_e32 v61, 0xffff0000, v40
	s_nop 0
	v_cndmask_b32_e64 v0, v0, v38, s[4:5]
	v_rsq_f32_e32 v0, v0
	s_nop 0
	v_mul_f32_e32 v38, 0x45800000, v0
	v_cndmask_b32_e64 v0, v0, v38, s[4:5]
	v_pk_mul_f32 v[38:39], v[0:1], v[42:43] op_sel_hi:[0,1]
	v_pk_mul_f32 v[28:29], v[0:1], v[28:29] op_sel_hi:[0,1]
	v_pk_mul_f32 v[46:47], v[0:1], v[46:47] op_sel_hi:[0,1]
	v_pk_mul_f32 v[30:31], v[0:1], v[30:31] op_sel_hi:[0,1]
	v_pk_mul_f32 v[48:49], v[0:1], v[48:49] op_sel_hi:[0,1]
	v_pk_mul_f32 v[32:33], v[0:1], v[32:33] op_sel_hi:[0,1]
	v_pk_mul_f32 v[50:51], v[0:1], v[50:51] op_sel_hi:[0,1]
	v_pk_mul_f32 v[26:27], v[0:1], v[26:27] op_sel_hi:[0,1]
	v_pk_fma_f32 v[42:43], v[10:11], v[38:39], v[52:53]
	v_pk_fma_f32 v[40:41], v[12:13], v[28:29], v[34:35]
	v_pk_fma_f32 v[38:39], v[2:3], v[46:47], v[54:55]
	v_pk_fma_f32 v[36:37], v[4:5], v[30:31], v[36:37]
	v_pk_fma_f32 v[34:35], v[6:7], v[48:49], v[56:57]
	v_pk_fma_f32 v[32:33], v[32:33], v[8:9], v[58:59]
	v_pk_fma_f32 v[30:31], v[50:51], v[14:15], v[60:61]
	v_pk_fma_f32 v[28:29], v[26:27], v[16:17], v[62:63]
	v_cvt_pk_bf16_f32 v26, v42, v43
	v_cvt_pk_bf16_f32 v27, v40, v41
	v_cvt_pk_bf16_f32 v46, v38, v39
	v_cvt_pk_bf16_f32 v47, v36, v37
	v_cvt_pk_bf16_f32 v48, v34, v35
	v_cvt_pk_bf16_f32 v49, v32, v33
	v_cvt_pk_bf16_f32 v50, v30, v31
	v_cvt_pk_bf16_f32 v51, v28, v29
	flat_store_dwordx2 v[44:45], v[26:27]
	flat_store_dwordx2 v[44:45], v[46:47] offset:512
	flat_store_dwordx2 v[44:45], v[48:49] offset:1024
	flat_store_dwordx2 v[44:45], v[50:51] offset:1536
	s_cbranch_vccnz .LBB0_3260
; DI void rowpass(const int wave_s, const float* __restrict__ xin, u16* __restrict__ X, const u16* __restrict__ Y, const float* __restrict__ gpost,
;                 const float* __restrict__ gpre, u16* __restrict__ HN, float* __restrict__ outf) {
;     ...
;     if (HN) {
;       ss2 = wsum(ss2);
;       const float rs2 = rsqrtf(ss2 * (1.f / 1024.f) + 1e-6f);
; #pragma unroll
;       for (int j = 0; j < 4; ++j) {
;         const float4 g = *(const float4*)(gpre + j * 256 + lane * 4);
;         uint2 pk;
;         pk.x = pack2(x[j].x * rs2 * g.x, x[j].y * rs2 * g.y);
;         pk.y = pack2(x[j].z * rs2 * g.z, x[j].w * rs2 * g.w);
;         *(uint2*)(HN + (size_t)row * 1024 + j * 256 + lane * 4) = pk;
;       }
	v_mov_b32_e32 v44, v43
	v_mov_b32_e32 v45, v39
	v_mov_b32_e32 v26, v42
	v_mov_b32_e32 v27, v38
	v_pk_mul_f32 v[44:45], v[44:45], v[44:45]
	v_mov_b32_e32 v46, v35
	v_pk_fma_f32 v[26:27], v[26:27], v[26:27], v[44:45]
	v_mov_b32_e32 v44, v40
	v_mov_b32_e32 v45, v36
	v_pk_fma_f32 v[26:27], v[44:45], v[44:45], v[26:27]
	v_mov_b32_e32 v44, v41
	v_mov_b32_e32 v45, v37
	v_mov_b32_e32 v47, v31
	v_pk_fma_f32 v[26:27], v[44:45], v[44:45], v[26:27]
	v_mov_b32_e32 v44, v34
	v_mov_b32_e32 v45, v30
	v_pk_mul_f32 v[46:47], v[46:47], v[46:47]
	v_add_f32_e32 v0, v26, v27
	v_pk_fma_f32 v[44:45], v[44:45], v[44:45], v[46:47]
	v_mov_b32_e32 v46, v32
	v_mov_b32_e32 v47, v28
	v_pk_fma_f32 v[44:45], v[46:47], v[46:47], v[44:45]
	v_mov_b32_e32 v46, v33
	v_mov_b32_e32 v47, v29
	v_pk_fma_f32 v[44:45], v[46:47], v[46:47], v[44:45]
	s_nop 0
	v_add_f32_e32 v0, v0, v44
	v_add_f32_e32 v0, v0, v45
	flat_load_dwordx4 v[44:47], v[22:23]
	v_mov_b32_e32 v26, v0
	s_nop 1
	v_permlane32_swap_b32_e32 v0, v26
	s_waitcnt lgkmcnt(0)
	v_add_f32_e32 v0, v0, v26
	v_mov_b32_e32 v26, v0
	s_nop 1
	v_permlane16_swap_b32_e32 v0, v26
	s_waitcnt lgkmcnt(0)
	v_add_f32_e32 v0, v0, v26
	s_nop 1
	v_mov_b32_dpp v26, v0 row_ror:8 row_mask:0xf bank_mask:0xf
	s_waitcnt lgkmcnt(0)
	v_add_f32_e32 v0, v0, v26
	s_nop 1
	v_mov_b32_dpp v26, v0 row_ror:4 row_mask:0xf bank_mask:0xf
	s_waitcnt lgkmcnt(0)
	v_add_f32_e32 v0, v0, v26
	s_nop 1
	v_mov_b32_dpp v26, v0 row_ror:2 row_mask:0xf bank_mask:0xf
	s_waitcnt lgkmcnt(0)
	v_add_f32_e32 v0, v0, v26
	s_nop 1
	v_mov_b32_dpp v26, v0 row_ror:1 row_mask:0xf bank_mask:0xf
	s_waitcnt lgkmcnt(0)
	v_add_f32_e32 v0, v0, v26
	v_fmamk_f32 v0, v0, 0x3a800000, v170
	v_cmp_gt_f32_e32 vcc, s16, v0
	v_mul_f32_e32 v26, 0x4b800000, v0
	s_nop 0
	v_cndmask_b32_e32 v0, v0, v26, vcc
	v_rsq_f32_e32 v0, v0
	s_nop 0
	v_mul_f32_e32 v26, 0x45800000, v0
	v_cndmask_b32_e32 v0, v0, v26, vcc
	v_pk_mul_f32 v[42:43], v[42:43], v[0:1] op_sel_hi:[1,0]
	v_pk_mul_f32 v[40:41], v[40:41], v[0:1] op_sel_hi:[1,0]
	v_lshl_add_u64 v[26:27], v[24:25], 0, s[14:15]
	v_pk_mul_f32 v[38:39], v[38:39], v[0:1] op_sel_hi:[1,0]
	v_pk_mul_f32 v[36:37], v[36:37], v[0:1] op_sel_hi:[1,0]
	v_pk_mul_f32 v[34:35], v[34:35], v[0:1] op_sel_hi:[1,0]
	v_pk_mul_f32 v[32:33], v[32:33], v[0:1] op_sel_hi:[1,0]
	v_pk_mul_f32 v[30:31], v[30:31], v[0:1] op_sel_hi:[1,0]
	v_pk_mul_f32 v[28:29], v[28:29], v[0:1] op_sel_hi:[1,0]
	s_waitcnt vmcnt(0)
	v_pk_mul_f32 v[42:43], v[44:45], v[42:43]
	v_pk_mul_f32 v[40:41], v[46:47], v[40:41]
	v_cvt_pk_bf16_f32 v42, v42, v43
	v_cvt_pk_bf16_f32 v43, v40, v41
	flat_store_dwordx2 v[26:27], v[42:43]
	flat_load_dwordx4 v[40:43], v[22:23] offset:1024
	s_waitcnt vmcnt(0) lgkmcnt(0)
	v_pk_mul_f32 v[38:39], v[40:41], v[38:39]
	v_pk_mul_f32 v[36:37], v[42:43], v[36:37]
	v_cvt_pk_bf16_f32 v38, v38, v39
	v_cvt_pk_bf16_f32 v39, v36, v37
	flat_store_dwordx2 v[26:27], v[38:39] offset:512
	flat_load_dwordx4 v[36:39], v[22:23] offset:2048
	s_waitcnt vmcnt(0) lgkmcnt(0)
	v_pk_mul_f32 v[34:35], v[34:35], v[36:37]
	v_pk_mul_f32 v[32:33], v[32:33], v[38:39]
	v_cvt_pk_bf16_f32 v34, v34, v35
	v_cvt_pk_bf16_f32 v35, v32, v33
	flat_store_dwordx2 v[26:27], v[34:35] offset:1024
	flat_load_dwordx4 v[32:35], v[22:23] offset:3072
	s_waitcnt vmcnt(0) lgkmcnt(0)
	v_pk_mul_f32 v[30:31], v[30:31], v[32:33]
	v_pk_mul_f32 v[28:29], v[28:29], v[34:35]
	v_cvt_pk_bf16_f32 v30, v30, v31
	v_cvt_pk_bf16_f32 v31, v28, v29
	flat_store_dwordx2 v[26:27], v[30:31] offset:1536
	s_branch .LBB0_3260

; #define MFMA32(a, b, c) __builtin_amdgcn_mfma_f32_32x32x16_bf16((a), (b), (c), 0, 0, 0)
; template <class AL, class EP>
; DI void gemm2(const int wave_s, const AL al, const u16* __restrict__ Wt, const int K, const int ntm, const int ntn, const EP ep, char* smem, const u16* zrow = nullptr) {
;     ...
;         const u16* ab = al.tilebase(tm, k0);
; #pragma unroll
;         for (int q = 0; q < 4; ++q) {
;           const u16* gp = (aoff[q] == 0xffffffffu) ? (zrow + scp * 8) : (ab + aoff[q]);
;           glds16(gp, sa + q * 1024);
;         }
;       } else {
; #pragma unroll
;         for (int i = 0; i < 4; ++i) ra[i] = al.load(tm, lrow + 64 * i, k0, lcp * 8);
;       }
;       const u16* wb = wbase + k0;
; #pragma unroll
;       for (int q = 0; q < 4; ++q) glds16(wb + woff[q], sa + 32768 + q * 1024);
;     ...
;       if (more) stage_issue(kt + 1, (kt + 1) & 1);
;       __builtin_amdgcn_sched_barrier(0);
;       const char* a = smem + (kt & 1) * G_STAGE_B + wm * 128 * 128;
;       const char* b = smem + (kt & 1) * G_STAGE_B + 32768 + wn * 64 * 128;
;       if constexpr (AL::DIRECT) {
;         bf16x8 af[2][4], bfr[2][2];
; #pragma unroll
;         for (int i = 0; i < 4; ++i) af[0][i] = *(const bf16x8*)(a + i * 4096 + foff[0]);
; #pragma unroll
;         for (int j = 0; j < 2; ++j) bfr[0][j] = *(const bf16x8*)(b + j * 4096 + foff[0]);
; #pragma unroll
;         for (int s = 0; s < 4; ++s) {
;           if (s < 3) {
; #pragma unroll
;             for (int i = 0; i < 4; ++i) af[(s + 1) & 1][i] = *(const bf16x8*)(a + i * 4096 + foff[s + 1]);
; #pragma unroll
;             for (int j = 0; j < 2; ++j) bfr[(s + 1) & 1][j] = *(const bf16x8*)(b + j * 4096 + foff[s + 1]);
;           }
;           __builtin_amdgcn_sched_barrier(0);
;           __builtin_amdgcn_s_setprio(1);
; #pragma unroll
;           for (int i = 0; i < 4; ++i) {
;             acc[i][0] = MFMA32(af[s & 1][i], bfr[s & 1][0], acc[i][0]);
;             acc[i][1] = MFMA32(af[s & 1][i], bfr[s & 1][1], acc[i][1]);
;           }
;           __builtin_amdgcn_s_setprio(0);
;           __builtin_amdgcn_sched_barrier(0);
;         }
.Lrot6_loop:
	s_setprio 1
	s_waitcnt lgkmcnt(6)
	v_mfma_f32_32x32x16_bf16 v[114:129], v[182:185], v[198:201], v[114:129]
	v_mfma_f32_32x32x16_bf16 v[98:113], v[182:185], v[202:205], v[98:113]
	v_mfma_f32_32x32x16_bf16 v[82:97], v[186:189], v[198:201], v[82:97]
	v_mfma_f32_32x32x16_bf16 v[66:81], v[186:189], v[202:205], v[66:81]
	v_mfma_f32_32x32x16_bf16 v[50:65], v[190:193], v[198:201], v[50:65]
	v_mfma_f32_32x32x16_bf16 v[34:49], v[190:193], v[202:205], v[34:49]
	v_mfma_f32_32x32x16_bf16 v[18:33], v[194:197], v[198:201], v[18:33]
	v_mfma_f32_32x32x16_bf16 v[2:17], v[194:197], v[202:205], v[2:17]
	s_setprio 0
	v_add_u32_e32 v181, s14, v172
	ds_read_b128 v[182:185], v181
	ds_read_b128 v[186:189], v181 offset:4096
	ds_read_b128 v[190:193], v181 offset:8192
	ds_read_b128 v[194:197], v181 offset:12288
	v_add_u32_e32 v181, s7, v172
	ds_read_b128 v[198:201], v181 offset:32768
	ds_read_b128 v[202:205], v181 offset:36864
	s_setprio 1
	s_waitcnt lgkmcnt(6)
	v_mfma_f32_32x32x16_bf16 v[114:129], v[206:209], v[222:225], v[114:129]
	v_mfma_f32_32x32x16_bf16 v[98:113], v[206:209], v[226:229], v[98:113]
	v_mfma_f32_32x32x16_bf16 v[82:97], v[210:213], v[222:225], v[82:97]
	v_mfma_f32_32x32x16_bf16 v[66:81], v[210:213], v[226:229], v[66:81]
	v_mfma_f32_32x32x16_bf16 v[50:65], v[214:217], v[222:225], v[50:65]
	v_mfma_f32_32x32x16_bf16 v[34:49], v[214:217], v[226:229], v[34:49]
	v_mfma_f32_32x32x16_bf16 v[18:33], v[218:221], v[222:225], v[18:33]
	v_mfma_f32_32x32x16_bf16 v[2:17], v[218:221], v[226:229], v[2:17]
	s_setprio 0
	v_add_u32_e32 v181, s14, v0
	ds_read_b128 v[206:209], v181
	ds_read_b128 v[210:213], v181 offset:4096
	ds_read_b128 v[214:217], v181 offset:8192
	ds_read_b128 v[218:221], v181 offset:12288
	v_add_u32_e32 v181, s7, v0
	ds_read_b128 v[222:225], v181 offset:32768
	ds_read_b128 v[226:229], v181 offset:36864
	s_add_i32 s5, s5, 0x10000
	s_and_b32 s14, s5, 0x10000
	s_add_i32 s7, s14, s19
	s_add_i32 s14, s14, s18
	s_cmp_eq_u32 s5, 0xf0000
	s_waitcnt vmcnt(0) lgkmcnt(0)
	s_barrier
	s_cbranch_scc1 .Lrot6_tail
	s_setprio 1
	s_add_i32 m0, s5, 0x10000
	s_and_b32 m0, m0, 0x10000
	s_add_i32 m0, m0, s17
	v_mfma_f32_32x32x16_bf16 v[114:129], v[182:185], v[198:201], v[114:129]
	global_load_lds_dwordx4 v[176:177], off
	v_lshl_add_u64 v[176:177], v[176:177], 0, s[8:9]
	s_add_i32 m0, m0, 0x400
	v_mfma_f32_32x32x16_bf16 v[98:113], v[182:185], v[202:205], v[98:113]
	v_mfma_f32_32x32x16_bf16 v[82:97], v[186:189], v[198:201], v[82:97]
	global_load_lds_dwordx4 v[168:169], off
	v_lshl_add_u64 v[168:169], v[168:169], 0, s[8:9]
	s_add_i32 m0, m0, 0x400
	v_mfma_f32_32x32x16_bf16 v[66:81], v[186:189], v[202:205], v[66:81]
	v_mfma_f32_32x32x16_bf16 v[50:65], v[190:193], v[198:201], v[50:65]
	global_load_lds_dwordx4 v[166:167], off
	v_lshl_add_u64 v[166:167], v[166:167], 0, s[8:9]
	s_add_i32 m0, m0, 0x400
	v_mfma_f32_32x32x16_bf16 v[34:49], v[190:193], v[202:205], v[34:49]
	v_mfma_f32_32x32x16_bf16 v[18:33], v[194:197], v[198:201], v[18:33]
	global_load_lds_dwordx4 v[164:165], off
	v_lshl_add_u64 v[164:165], v[164:165], 0, s[8:9]
	s_add_i32 m0, m0, 0x7400
	v_mfma_f32_32x32x16_bf16 v[2:17], v[194:197], v[202:205], v[2:17]
	s_setprio 0
	v_add_u32_e32 v181, s14, v178
	ds_read_b128 v[182:185], v181
	ds_read_b128 v[186:189], v181 offset:4096
	ds_read_b128 v[190:193], v181 offset:8192
	ds_read_b128 v[194:197], v181 offset:12288
	v_add_u32_e32 v181, s7, v178
	ds_read_b128 v[198:201], v181 offset:32768
	ds_read_b128 v[202:205], v181 offset:36864
	s_setprio 1
	v_mfma_f32_32x32x16_bf16 v[114:129], v[206:209], v[222:225], v[114:129]
	global_load_lds_dwordx4 v[162:163], off
	v_lshl_add_u64 v[162:163], v[162:163], 0, s[8:9]
	s_add_i32 m0, m0, 0x400
	v_mfma_f32_32x32x16_bf16 v[98:113], v[206:209], v[226:229], v[98:113]
	v_mfma_f32_32x32x16_bf16 v[82:97], v[210:213], v[222:225], v[82:97]
	global_load_lds_dwordx4 v[160:161], off
	v_lshl_add_u64 v[160:161], v[160:161], 0, s[8:9]
	s_add_i32 m0, m0, 0x400
	v_mfma_f32_32x32x16_bf16 v[66:81], v[210:213], v[226:229], v[66:81]
	v_mfma_f32_32x32x16_bf16 v[50:65], v[214:217], v[222:225], v[50:65]
	global_load_lds_dwordx4 v[158:159], off
	v_lshl_add_u64 v[158:159], v[158:159], 0, s[8:9]
	s_add_i32 m0, m0, 0x400
	v_mfma_f32_32x32x16_bf16 v[34:49], v[214:217], v[226:229], v[34:49]
	v_mfma_f32_32x32x16_bf16 v[18:33], v[218:221], v[222:225], v[18:33]
	global_load_lds_dwordx4 v[156:157], off
	v_lshl_add_u64 v[156:157], v[156:157], 0, s[8:9]
	v_mfma_f32_32x32x16_bf16 v[2:17], v[218:221], v[226:229], v[2:17]
	s_setprio 0
	v_add_u32_e32 v181, s14, v175
	ds_read_b128 v[206:209], v181
	ds_read_b128 v[210:213], v181 offset:4096
	ds_read_b128 v[214:217], v181 offset:8192
	ds_read_b128 v[218:221], v181 offset:12288
	v_add_u32_e32 v181, s7, v175
	ds_read_b128 v[222:225], v181 offset:32768
	ds_read_b128 v[226:229], v181 offset:36864
	s_branch .Lrot6_loop

; #define MFMA32(a, b, c) __builtin_amdgcn_mfma_f32_32x32x16_bf16((a), (b), (c), 0, 0, 0)
; template <class AL, class EP>
; DI void gemm2(const int wave_s, const AL al, const u16* __restrict__ Wt, const int K, const int ntm, const int ntn, const EP ep, char* smem, const u16* zrow = nullptr) {
;     ...
;         const u16* ab = al.tilebase(tm, k0);
; #pragma unroll
;         for (int q = 0; q < 4; ++q) {
;           const u16* gp = (aoff[q] == 0xffffffffu) ? (zrow + scp * 8) : (ab + aoff[q]);
;           glds16(gp, sa + q * 1024);
;         }
;       } else {
; #pragma unroll
;         for (int i = 0; i < 4; ++i) ra[i] = al.load(tm, lrow + 64 * i, k0, lcp * 8);
;       }
;       const u16* wb = wbase + k0;
; #pragma unroll
;       for (int q = 0; q < 4; ++q) glds16(wb + woff[q], sa + 32768 + q * 1024);
;     ...
;       if (more) stage_issue(kt + 1, (kt + 1) & 1);
;       __builtin_amdgcn_sched_barrier(0);
;       const char* a = smem + (kt & 1) * G_STAGE_B + wm * 128 * 128;
;       const char* b = smem + (kt & 1) * G_STAGE_B + 32768 + wn * 64 * 128;
;       if constexpr (AL::DIRECT) {
;         bf16x8 af[2][4], bfr[2][2];
; #pragma unroll
;         for (int i = 0; i < 4; ++i) af[0][i] = *(const bf16x8*)(a + i * 4096 + foff[0]);
; #pragma unroll
;         for (int j = 0; j < 2; ++j) bfr[0][j] = *(const bf16x8*)(b + j * 4096 + foff[0]);
; #pragma unroll
;         for (int s = 0; s < 4; ++s) {
;           if (s < 3) {
; #pragma unroll
;             for (int i = 0; i < 4; ++i) af[(s + 1) & 1][i] = *(const bf16x8*)(a + i * 4096 + foff[s + 1]);
; #pragma unroll
;             for (int j = 0; j < 2; ++j) bfr[(s + 1) & 1][j] = *(const bf16x8*)(b + j * 4096 + foff[s + 1]);
;           }
;           __builtin_amdgcn_sched_barrier(0);
;           __builtin_amdgcn_s_setprio(1);
; #pragma unroll
;           for (int i = 0; i < 4; ++i) {
;             acc[i][0] = MFMA32(af[s & 1][i], bfr[s & 1][0], acc[i][0]);
;             acc[i][1] = MFMA32(af[s & 1][i], bfr[s & 1][1], acc[i][1]);
;           }
;           __builtin_amdgcn_s_setprio(0);
;           __builtin_amdgcn_sched_barrier(0);
;         }
.Lrot7_loop:
	s_setprio 1
	s_waitcnt lgkmcnt(6)
	v_mfma_f32_32x32x16_bf16 v[114:129], v[182:185], v[198:201], v[114:129]
	v_mfma_f32_32x32x16_bf16 v[98:113], v[182:185], v[202:205], v[98:113]
	v_mfma_f32_32x32x16_bf16 v[82:97], v[186:189], v[198:201], v[82:97]
	v_mfma_f32_32x32x16_bf16 v[66:81], v[186:189], v[202:205], v[66:81]
	v_mfma_f32_32x32x16_bf16 v[50:65], v[190:193], v[198:201], v[50:65]
	v_mfma_f32_32x32x16_bf16 v[34:49], v[190:193], v[202:205], v[34:49]
	v_mfma_f32_32x32x16_bf16 v[18:33], v[194:197], v[198:201], v[18:33]
	v_mfma_f32_32x32x16_bf16 v[2:17], v[194:197], v[202:205], v[2:17]
	s_setprio 0
	v_add_u32_e32 v181, s18, v172
	ds_read_b128 v[182:185], v181
	ds_read_b128 v[186:189], v181 offset:4096
	ds_read_b128 v[190:193], v181 offset:8192
	ds_read_b128 v[194:197], v181 offset:12288
	v_add_u32_e32 v181, s7, v172
	ds_read_b128 v[198:201], v181 offset:32768
	ds_read_b128 v[202:205], v181 offset:36864
	s_setprio 1
	s_waitcnt lgkmcnt(6)
	v_mfma_f32_32x32x16_bf16 v[114:129], v[206:209], v[222:225], v[114:129]
	v_mfma_f32_32x32x16_bf16 v[98:113], v[206:209], v[226:229], v[98:113]
	v_mfma_f32_32x32x16_bf16 v[82:97], v[210:213], v[222:225], v[82:97]
	v_mfma_f32_32x32x16_bf16 v[66:81], v[210:213], v[226:229], v[66:81]
	v_mfma_f32_32x32x16_bf16 v[50:65], v[214:217], v[222:225], v[50:65]
	v_mfma_f32_32x32x16_bf16 v[34:49], v[214:217], v[226:229], v[34:49]
	v_mfma_f32_32x32x16_bf16 v[18:33], v[218:221], v[222:225], v[18:33]
	v_mfma_f32_32x32x16_bf16 v[2:17], v[218:221], v[226:229], v[2:17]
	s_setprio 0
	v_add_u32_e32 v181, s18, v0
	ds_read_b128 v[206:209], v181
	ds_read_b128 v[210:213], v181 offset:4096
	ds_read_b128 v[214:217], v181 offset:8192
	ds_read_b128 v[218:221], v181 offset:12288
	v_add_u32_e32 v181, s7, v0
	ds_read_b128 v[222:225], v181 offset:32768
	ds_read_b128 v[226:229], v181 offset:36864
	s_add_i32 s5, s5, 0x10000
	s_and_b32 s18, s5, 0x10000
	s_add_i32 s7, s18, s25
	s_add_i32 s18, s18, s24
	s_cmp_eq_u32 s5, 0x70000
	s_waitcnt vmcnt(0) lgkmcnt(0)
	s_barrier
	s_cbranch_scc1 .Lrot7_tail
	s_setprio 1
	s_add_i32 m0, s5, 0x10000
	s_and_b32 m0, m0, 0x10000
	s_add_i32 m0, m0, s23
	v_mfma_f32_32x32x16_bf16 v[114:129], v[182:185], v[198:201], v[114:129]
	global_load_lds_dwordx4 v[176:177], off
	v_lshl_add_u64 v[176:177], v[176:177], 0, s[16:17]
	s_add_i32 m0, m0, 0x400
	v_mfma_f32_32x32x16_bf16 v[98:113], v[182:185], v[202:205], v[98:113]
	v_mfma_f32_32x32x16_bf16 v[82:97], v[186:189], v[198:201], v[82:97]
	global_load_lds_dwordx4 v[168:169], off
	v_lshl_add_u64 v[168:169], v[168:169], 0, s[16:17]
	s_add_i32 m0, m0, 0x400
	v_mfma_f32_32x32x16_bf16 v[66:81], v[186:189], v[202:205], v[66:81]
	v_mfma_f32_32x32x16_bf16 v[50:65], v[190:193], v[198:201], v[50:65]
	global_load_lds_dwordx4 v[166:167], off
	v_lshl_add_u64 v[166:167], v[166:167], 0, s[16:17]
	s_add_i32 m0, m0, 0x400
	v_mfma_f32_32x32x16_bf16 v[34:49], v[190:193], v[202:205], v[34:49]
	v_mfma_f32_32x32x16_bf16 v[18:33], v[194:197], v[198:201], v[18:33]
	global_load_lds_dwordx4 v[164:165], off
	v_lshl_add_u64 v[164:165], v[164:165], 0, s[16:17]
	s_add_i32 m0, m0, 0x7400
	v_mfma_f32_32x32x16_bf16 v[2:17], v[194:197], v[202:205], v[2:17]
	s_setprio 0
	v_add_u32_e32 v181, s18, v178
	ds_read_b128 v[182:185], v181
	ds_read_b128 v[186:189], v181 offset:4096
	ds_read_b128 v[190:193], v181 offset:8192
	ds_read_b128 v[194:197], v181 offset:12288
	v_add_u32_e32 v181, s7, v178
	ds_read_b128 v[198:201], v181 offset:32768
	ds_read_b128 v[202:205], v181 offset:36864
	s_setprio 1
	v_mfma_f32_32x32x16_bf16 v[114:129], v[206:209], v[222:225], v[114:129]
	global_load_lds_dwordx4 v[162:163], off
	v_lshl_add_u64 v[162:163], v[162:163], 0, s[16:17]
	s_add_i32 m0, m0, 0x400
	v_mfma_f32_32x32x16_bf16 v[98:113], v[206:209], v[226:229], v[98:113]
	v_mfma_f32_32x32x16_bf16 v[82:97], v[210:213], v[222:225], v[82:97]
	global_load_lds_dwordx4 v[160:161], off
	v_lshl_add_u64 v[160:161], v[160:161], 0, s[16:17]
	s_add_i32 m0, m0, 0x400
	v_mfma_f32_32x32x16_bf16 v[66:81], v[210:213], v[226:229], v[66:81]
	v_mfma_f32_32x32x16_bf16 v[50:65], v[214:217], v[222:225], v[50:65]
	global_load_lds_dwordx4 v[158:159], off
	v_lshl_add_u64 v[158:159], v[158:159], 0, s[16:17]
	s_add_i32 m0, m0, 0x400
	v_mfma_f32_32x32x16_bf16 v[34:49], v[214:217], v[226:229], v[34:49]
	v_mfma_f32_32x32x16_bf16 v[18:33], v[218:221], v[222:225], v[18:33]
	global_load_lds_dwordx4 v[156:157], off
	v_lshl_add_u64 v[156:157], v[156:157], 0, s[16:17]
	v_mfma_f32_32x32x16_bf16 v[2:17], v[218:221], v[226:229], v[2:17]
	s_setprio 0
	v_add_u32_e32 v181, s18, v175
	ds_read_b128 v[206:209], v181
	ds_read_b128 v[210:213], v181 offset:4096
	ds_read_b128 v[214:217], v181 offset:8192
	ds_read_b128 v[218:221], v181 offset:12288
	v_add_u32_e32 v181, s7, v175
	ds_read_b128 v[222:225], v181 offset:32768
	ds_read_b128 v[226:229], v181 offset:36864
	s_branch .Lrot7_loop

; DI float bflo(unsigned u) { return __uint_as_float(u << 16); }
; DI float bfhi(unsigned u) { return __uint_as_float(u & 0xffff0000u); }
; DI void rowpass(const int wave_s, const float* __restrict__ xin, u16* __restrict__ X, const u16* __restrict__ Y, const float* __restrict__ gpost,
;                 const float* __restrict__ gpre, u16* __restrict__ HN, float* __restrict__ outf) {
;     ...
;     if (Y) {
;       float4 y[4];
;       float ss = 0.f;
; #pragma unroll
;       for (int j = 0; j < 4; ++j) {
;         const uint2 yu = *(const uint2*)(Y + (size_t)row * 1024 + j * 256 + lane * 4);
;         y[j] = make_float4(bflo(yu.x), bfhi(yu.x), bflo(yu.y), bfhi(yu.y));
;         ss += y[j].x * y[j].x + y[j].y * y[j].y + y[j].z * y[j].z + y[j].w * y[j].w;
;       }
;       ss = wsum(ss);
;       const float rs = rsqrtf(ss * (1.f / 1024.f) + 1e-6f);
; #pragma unroll
;       for (int j = 0; j < 4; ++j) {
;         const float4 g = *(const float4*)(gpost + j * 256 + lane * 4);
;         const uint2 xu = *(const uint2*)(X + (size_t)row * 1024 + j * 256 + lane * 4);
;         x[j] = make_float4(bflo(xu.x), bfhi(xu.x), bflo(xu.y), bfhi(xu.y));
;         x[j].x += y[j].x * rs * g.x; x[j].y += y[j].y * rs * g.y; x[j].z += y[j].z * rs * g.z; x[j].w += y[j].w * rs * g.w;
;       }
;     } else {
; #pragma unroll
;       for (int j = 0; j < 4; ++j) x[j] = *(const float4*)(xin + (size_t)row * 1024 + j * 256 + lane * 4);
;     }
;     float ss2 = 0.f;
; #pragma unroll
;     for (int j = 0; j < 4; ++j) {
;       if (outf) *(float4*)(outf + (size_t)row * 1024 + j * 256 + lane * 4) = x[j];
;       else { uint2 xp; xp.x = pack2(x[j].x, x[j].y); xp.y = pack2(x[j].z, x[j].w); *(uint2*)(X + (size_t)row * 1024 + j * 256 + lane * 4) = xp; }
;       ss2 += x[j].x * x[j].x + x[j].y * x[j].y + x[j].z * x[j].z + x[j].w * x[j].w;
.LBB0_3528:
	s_ashr_i32 s7, s6, 31
	s_lshl_b64 s[14:15], s[6:7], 11
	v_lshl_add_u64 v[26:27], v[18:19], 0, s[14:15]
	flat_load_dwordx2 v[28:29], v[26:27]
	flat_load_dwordx2 v[30:31], v[26:27] offset:512
	flat_load_dwordx2 v[32:33], v[26:27] offset:1024
	s_nop 0
	flat_load_dwordx2 v[26:27], v[26:27] offset:1536
	v_lshl_add_u64 v[44:45], v[20:21], 0, s[14:15]
	flat_load_dwordx2 v[34:35], v[44:45]
	flat_load_dwordx2 v[36:37], v[44:45] offset:512
	flat_load_dwordx2 v[38:39], v[44:45] offset:1024
	flat_load_dwordx2 v[40:41], v[44:45] offset:1536
	s_mov_b32 s7, 0x800000
	s_andn2_b64 vcc, exec, s[8:9]
	s_waitcnt vmcnt(0) lgkmcnt(0)
	v_and_b32_e32 v43, 0xffff0000, v28
	v_and_b32_e32 v47, 0xffff0000, v30
	v_lshlrev_b32_e32 v42, 16, v28
	v_lshlrev_b32_e32 v46, 16, v30
	v_and_b32_e32 v49, 0xffff0000, v32
	v_and_b32_e32 v51, 0xffff0000, v26
	v_mov_b32_e32 v58, v43
	v_mov_b32_e32 v59, v47
	v_lshlrev_b32_e32 v28, 16, v29
	v_lshlrev_b32_e32 v30, 16, v31
	v_lshlrev_b32_e32 v48, 16, v32
	v_lshlrev_b32_e32 v50, 16, v26
	v_mov_b32_e32 v56, v42
	v_mov_b32_e32 v57, v46
	v_mov_b32_e32 v66, v49
	v_mov_b32_e32 v67, v51
	v_pk_mul_f32 v[58:59], v[58:59], v[58:59]
	v_and_b32_e32 v29, 0xffff0000, v29
	v_and_b32_e32 v31, 0xffff0000, v31
	v_lshlrev_b32_e32 v32, 16, v33
	v_lshlrev_b32_e32 v26, 16, v27
	v_mov_b32_e32 v52, v28
	v_mov_b32_e32 v53, v30
	v_mov_b32_e32 v64, v48
	v_mov_b32_e32 v65, v50
	v_pk_mul_f32 v[66:67], v[66:67], v[66:67]
	v_pk_fma_f32 v[56:57], v[56:57], v[56:57], v[58:59]
	v_and_b32_e32 v33, 0xffff0000, v33
	v_and_b32_e32 v27, 0xffff0000, v27
	v_mov_b32_e32 v54, v29
	v_mov_b32_e32 v55, v31
	v_mov_b32_e32 v60, v32
	v_mov_b32_e32 v61, v26
	v_pk_fma_f32 v[58:59], v[64:65], v[64:65], v[66:67]
	v_pk_fma_f32 v[52:53], v[52:53], v[52:53], v[56:57]
	v_mov_b32_e32 v62, v33
	v_mov_b32_e32 v63, v27
	v_pk_fma_f32 v[56:57], v[60:61], v[60:61], v[58:59]
	v_pk_fma_f32 v[52:53], v[54:55], v[54:55], v[52:53]
	v_pk_fma_f32 v[54:55], v[62:63], v[62:63], v[56:57]
	v_add_f32_e32 v0, v52, v53
	v_add_f32_e32 v0, v0, v54
	v_add_f32_e32 v0, v0, v55
	v_mov_b32_e32 v52, v0
	s_nop 1
	v_permlane32_swap_b32_e32 v0, v52
	v_lshlrev_b32_e32 v56, 16, v38
	v_lshlrev_b32_e32 v58, 16, v39
	v_and_b32_e32 v59, 0xffff0000, v39
	v_lshlrev_b32_e32 v54, 16, v36
	s_waitcnt lgkmcnt(0)
	v_add_f32_e32 v0, v0, v52
	v_mov_b32_e32 v52, v0
	s_nop 1
	v_permlane16_swap_b32_e32 v0, v52
	v_lshlrev_b32_e32 v60, 16, v40
	v_lshlrev_b32_e32 v62, 16, v41
	v_and_b32_e32 v63, 0xffff0000, v41
	s_waitcnt lgkmcnt(0)
	v_add_f32_e32 v0, v0, v52
	s_nop 1
	v_mov_b32_dpp v53, v0 row_ror:8 row_mask:0xf bank_mask:0xf
	v_lshlrev_b32_e32 v52, 16, v34
	s_waitcnt lgkmcnt(0)
	v_add_f32_e32 v0, v0, v53
	s_nop 1
	v_mov_b32_dpp v55, v0 row_ror:4 row_mask:0xf bank_mask:0xf
	v_and_b32_e32 v53, 0xffff0000, v34
	v_lshlrev_b32_e32 v34, 16, v35
	v_and_b32_e32 v35, 0xffff0000, v35
	s_waitcnt lgkmcnt(0)
	v_add_f32_e32 v0, v0, v55
	s_nop 1
	v_mov_b32_dpp v57, v0 row_ror:2 row_mask:0xf bank_mask:0xf
	v_and_b32_e32 v55, 0xffff0000, v36
	v_lshlrev_b32_e32 v36, 16, v37
	v_and_b32_e32 v37, 0xffff0000, v37
	s_waitcnt lgkmcnt(0)
	v_add_f32_e32 v0, v0, v57
	s_nop 1
	v_mov_b32_dpp v61, v0 row_ror:1 row_mask:0xf bank_mask:0xf
	v_and_b32_e32 v57, 0xffff0000, v38
	s_waitcnt lgkmcnt(0)
	v_add_f32_e32 v0, v0, v61
	v_fmamk_f32 v0, v0, 0x3a800000, v170
	v_mul_f32_e32 v38, 0x4b800000, v0
	v_cmp_gt_f32_e64 s[4:5], s7, v0
	v_and_b32_e32 v61, 0xffff0000, v40
	s_nop 0
	v_cndmask_b32_e64 v0, v0, v38, s[4:5]
	v_rsq_f32_e32 v0, v0
	s_nop 0
	v_mul_f32_e32 v38, 0x45800000, v0
	v_cndmask_b32_e64 v0, v0, v38, s[4:5]
	v_pk_mul_f32 v[38:39], v[0:1], v[42:43] op_sel_hi:[0,1]
	v_pk_mul_f32 v[28:29], v[0:1], v[28:29] op_sel_hi:[0,1]
	v_pk_mul_f32 v[46:47], v[0:1], v[46:47] op_sel_hi:[0,1]
	v_pk_mul_f32 v[30:31], v[0:1], v[30:31] op_sel_hi:[0,1]
	v_pk_mul_f32 v[48:49], v[0:1], v[48:49] op_sel_hi:[0,1]
	v_pk_mul_f32 v[32:33], v[0:1], v[32:33] op_sel_hi:[0,1]
	v_pk_mul_f32 v[50:51], v[0:1], v[50:51] op_sel_hi:[0,1]
	v_pk_mul_f32 v[26:27], v[0:1], v[26:27] op_sel_hi:[0,1]
	v_pk_fma_f32 v[42:43], v[10:11], v[38:39], v[52:53]
	v_pk_fma_f32 v[40:41], v[12:13], v[28:29], v[34:35]
	v_pk_fma_f32 v[38:39], v[2:3], v[46:47], v[54:55]
	v_pk_fma_f32 v[36:37], v[4:5], v[30:31], v[36:37]
	v_pk_fma_f32 v[34:35], v[6:7], v[48:49], v[56:57]
	v_pk_fma_f32 v[32:33], v[32:33], v[8:9], v[58:59]
	v_pk_fma_f32 v[30:31], v[50:51], v[14:15], v[60:61]
	v_pk_fma_f32 v[28:29], v[26:27], v[16:17], v[62:63]
	v_cvt_pk_bf16_f32 v26, v42, v43
	v_cvt_pk_bf16_f32 v27, v40, v41
	v_cvt_pk_bf16_f32 v46, v38, v39
	v_cvt_pk_bf16_f32 v47, v36, v37
	v_cvt_pk_bf16_f32 v48, v34, v35
	v_cvt_pk_bf16_f32 v49, v32, v33
	v_cvt_pk_bf16_f32 v50, v30, v31
	v_cvt_pk_bf16_f32 v51, v28, v29
	flat_store_dwordx2 v[44:45], v[26:27]
	flat_store_dwordx2 v[44:45], v[46:47] offset:512
	flat_store_dwordx2 v[44:45], v[48:49] offset:1024
	flat_store_dwordx2 v[44:45], v[50:51] offset:1536
	s_cbranch_vccnz .LBB0_3527
; DI void rowpass(const int wave_s, const float* __restrict__ xin, u16* __restrict__ X, const u16* __restrict__ Y, const float* __restrict__ gpost,
;                 const float* __restrict__ gpre, u16* __restrict__ HN, float* __restrict__ outf) {
;     ...
;     if (HN) {
;       ss2 = wsum(ss2);
;       const float rs2 = rsqrtf(ss2 * (1.f / 1024.f) + 1e-6f);
; #pragma unroll
;       for (int j = 0; j < 4; ++j) {
;         const float4 g = *(const float4*)(gpre + j * 256 + lane * 4);
;         uint2 pk;
;         pk.x = pack2(x[j].x * rs2 * g.x, x[j].y * rs2 * g.y);
;         pk.y = pack2(x[j].z * rs2 * g.z, x[j].w * rs2 * g.w);
;         *(uint2*)(HN + (size_t)row * 1024 + j * 256 + lane * 4) = pk;
;       }
	v_mov_b32_e32 v44, v43
	v_mov_b32_e32 v45, v39
	v_mov_b32_e32 v26, v42
	v_mov_b32_e32 v27, v38
	v_pk_mul_f32 v[44:45], v[44:45], v[44:45]
	v_mov_b32_e32 v46, v35
	v_pk_fma_f32 v[26:27], v[26:27], v[26:27], v[44:45]
	v_mov_b32_e32 v44, v40
	v_mov_b32_e32 v45, v36
	v_pk_fma_f32 v[26:27], v[44:45], v[44:45], v[26:27]
	v_mov_b32_e32 v44, v41
	v_mov_b32_e32 v45, v37
	v_mov_b32_e32 v47, v31
	v_pk_fma_f32 v[26:27], v[44:45], v[44:45], v[26:27]
	v_mov_b32_e32 v44, v34
	v_mov_b32_e32 v45, v30
	v_pk_mul_f32 v[46:47], v[46:47], v[46:47]
	v_add_f32_e32 v0, v26, v27
	v_pk_fma_f32 v[44:45], v[44:45], v[44:45], v[46:47]
	v_mov_b32_e32 v46, v32
	v_mov_b32_e32 v47, v28
	v_pk_fma_f32 v[44:45], v[46:47], v[46:47], v[44:45]
	v_mov_b32_e32 v46, v33
	v_mov_b32_e32 v47, v29
	v_pk_fma_f32 v[44:45], v[46:47], v[46:47], v[44:45]
	s_nop 0
	v_add_f32_e32 v0, v0, v44
	v_add_f32_e32 v0, v0, v45
	flat_load_dwordx4 v[44:47], v[22:23]
	v_mov_b32_e32 v26, v0
	s_nop 1
	v_permlane32_swap_b32_e32 v0, v26
	s_waitcnt lgkmcnt(0)
	v_add_f32_e32 v0, v0, v26
	v_mov_b32_e32 v26, v0
	s_nop 1
	v_permlane16_swap_b32_e32 v0, v26
	s_waitcnt lgkmcnt(0)
	v_add_f32_e32 v0, v0, v26
	s_nop 1
	v_mov_b32_dpp v26, v0 row_ror:8 row_mask:0xf bank_mask:0xf
	s_waitcnt lgkmcnt(0)
	v_add_f32_e32 v0, v0, v26
	s_nop 1
	v_mov_b32_dpp v26, v0 row_ror:4 row_mask:0xf bank_mask:0xf
	s_waitcnt lgkmcnt(0)
	v_add_f32_e32 v0, v0, v26
	s_nop 1
	v_mov_b32_dpp v26, v0 row_ror:2 row_mask:0xf bank_mask:0xf
	s_waitcnt lgkmcnt(0)
	v_add_f32_e32 v0, v0, v26
	s_nop 1
	v_mov_b32_dpp v26, v0 row_ror:1 row_mask:0xf bank_mask:0xf
	s_waitcnt lgkmcnt(0)
	v_add_f32_e32 v0, v0, v26
	v_fmamk_f32 v0, v0, 0x3a800000, v170
	v_cmp_gt_f32_e32 vcc, s7, v0
	v_mul_f32_e32 v26, 0x4b800000, v0
	s_nop 0
	v_cndmask_b32_e32 v0, v0, v26, vcc
	v_rsq_f32_e32 v0, v0
	s_nop 0
	v_mul_f32_e32 v26, 0x45800000, v0
	v_cndmask_b32_e32 v0, v0, v26, vcc
	v_pk_mul_f32 v[42:43], v[42:43], v[0:1] op_sel_hi:[1,0]
	v_pk_mul_f32 v[40:41], v[40:41], v[0:1] op_sel_hi:[1,0]
	v_lshl_add_u64 v[26:27], v[24:25], 0, s[14:15]
	v_pk_mul_f32 v[38:39], v[38:39], v[0:1] op_sel_hi:[1,0]
	v_pk_mul_f32 v[36:37], v[36:37], v[0:1] op_sel_hi:[1,0]
	v_pk_mul_f32 v[34:35], v[34:35], v[0:1] op_sel_hi:[1,0]
	v_pk_mul_f32 v[32:33], v[32:33], v[0:1] op_sel_hi:[1,0]
	v_pk_mul_f32 v[30:31], v[30:31], v[0:1] op_sel_hi:[1,0]
	v_pk_mul_f32 v[28:29], v[28:29], v[0:1] op_sel_hi:[1,0]
	s_waitcnt vmcnt(0)
	v_pk_mul_f32 v[42:43], v[44:45], v[42:43]
	v_pk_mul_f32 v[40:41], v[46:47], v[40:41]
	v_cvt_pk_bf16_f32 v42, v42, v43
	v_cvt_pk_bf16_f32 v43, v40, v41
	flat_store_dwordx2 v[26:27], v[42:43]
	flat_load_dwordx4 v[40:43], v[22:23] offset:1024
	s_waitcnt vmcnt(0) lgkmcnt(0)
	v_pk_mul_f32 v[38:39], v[40:41], v[38:39]
	v_pk_mul_f32 v[36:37], v[42:43], v[36:37]
	v_cvt_pk_bf16_f32 v38, v38, v39
	v_cvt_pk_bf16_f32 v39, v36, v37
	flat_store_dwordx2 v[26:27], v[38:39] offset:512
	flat_load_dwordx4 v[36:39], v[22:23] offset:2048
	s_waitcnt vmcnt(0) lgkmcnt(0)
	v_pk_mul_f32 v[34:35], v[34:35], v[36:37]
	v_pk_mul_f32 v[32:33], v[32:33], v[38:39]
	v_cvt_pk_bf16_f32 v34, v34, v35
	v_cvt_pk_bf16_f32 v35, v32, v33
	flat_store_dwordx2 v[26:27], v[34:35] offset:1024
	flat_load_dwordx4 v[32:35], v[22:23] offset:3072
	s_waitcnt vmcnt(0) lgkmcnt(0)
	v_pk_mul_f32 v[30:31], v[30:31], v[32:33]
	v_pk_mul_f32 v[28:29], v[28:29], v[34:35]
	v_cvt_pk_bf16_f32 v30, v30, v31
	v_cvt_pk_bf16_f32 v31, v28, v29
	flat_store_dwordx2 v[26:27], v[30:31] offset:1536
	s_branch .LBB0_3527

; #define MFMA32(a, b, c) __builtin_amdgcn_mfma_f32_32x32x16_bf16((a), (b), (c), 0, 0, 0)
; template <class AL, class EP>
; DI void gemm2(const int wave_s, const AL al, const u16* __restrict__ Wt, const int K, const int ntm, const int ntn, const EP ep, char* smem, const u16* zrow = nullptr) {
;     ...
;         const u16* ab = al.tilebase(tm, k0);
; #pragma unroll
;         for (int q = 0; q < 4; ++q) {
;           const u16* gp = (aoff[q] == 0xffffffffu) ? (zrow + scp * 8) : (ab + aoff[q]);
;           glds16(gp, sa + q * 1024);
;         }
;       } else {
; #pragma unroll
;         for (int i = 0; i < 4; ++i) ra[i] = al.load(tm, lrow + 64 * i, k0, lcp * 8);
;       }
;       const u16* wb = wbase + k0;
; #pragma unroll
;       for (int q = 0; q < 4; ++q) glds16(wb + woff[q], sa + 32768 + q * 1024);
;     ...
;       if (more) stage_issue(kt + 1, (kt + 1) & 1);
;       __builtin_amdgcn_sched_barrier(0);
;       const char* a = smem + (kt & 1) * G_STAGE_B + wm * 128 * 128;
;       const char* b = smem + (kt & 1) * G_STAGE_B + 32768 + wn * 64 * 128;
;       if constexpr (AL::DIRECT) {
;         bf16x8 af[2][4], bfr[2][2];
; #pragma unroll
;         for (int i = 0; i < 4; ++i) af[0][i] = *(const bf16x8*)(a + i * 4096 + foff[0]);
; #pragma unroll
;         for (int j = 0; j < 2; ++j) bfr[0][j] = *(const bf16x8*)(b + j * 4096 + foff[0]);
; #pragma unroll
;         for (int s = 0; s < 4; ++s) {
;           if (s < 3) {
; #pragma unroll
;             for (int i = 0; i < 4; ++i) af[(s + 1) & 1][i] = *(const bf16x8*)(a + i * 4096 + foff[s + 1]);
; #pragma unroll
;             for (int j = 0; j < 2; ++j) bfr[(s + 1) & 1][j] = *(const bf16x8*)(b + j * 4096 + foff[s + 1]);
;           }
;           __builtin_amdgcn_sched_barrier(0);
;           __builtin_amdgcn_s_setprio(1);
; #pragma unroll
;           for (int i = 0; i < 4; ++i) {
;             acc[i][0] = MFMA32(af[s & 1][i], bfr[s & 1][0], acc[i][0]);
;             acc[i][1] = MFMA32(af[s & 1][i], bfr[s & 1][1], acc[i][1]);
;           }
;           __builtin_amdgcn_s_setprio(0);
;           __builtin_amdgcn_sched_barrier(0);
;         }
.Lrot9_loop:
	s_setprio 1
	s_waitcnt lgkmcnt(6)
	v_mfma_f32_32x32x16_bf16 v[114:129], v[182:185], v[198:201], v[114:129]
	v_mfma_f32_32x32x16_bf16 v[98:113], v[182:185], v[202:205], v[98:113]
	v_mfma_f32_32x32x16_bf16 v[82:97], v[186:189], v[198:201], v[82:97]
	v_mfma_f32_32x32x16_bf16 v[66:81], v[186:189], v[202:205], v[66:81]
	v_mfma_f32_32x32x16_bf16 v[50:65], v[190:193], v[198:201], v[50:65]
	v_mfma_f32_32x32x16_bf16 v[34:49], v[190:193], v[202:205], v[34:49]
	v_mfma_f32_32x32x16_bf16 v[18:33], v[194:197], v[198:201], v[18:33]
	v_mfma_f32_32x32x16_bf16 v[2:17], v[194:197], v[202:205], v[2:17]
	s_setprio 0
	v_add_u32_e32 v181, s16, v172
	ds_read_b128 v[182:185], v181
	ds_read_b128 v[186:189], v181 offset:4096
	ds_read_b128 v[190:193], v181 offset:8192
	ds_read_b128 v[194:197], v181 offset:12288
	v_add_u32_e32 v181, s15, v172
	ds_read_b128 v[198:201], v181 offset:32768
	ds_read_b128 v[202:205], v181 offset:36864
	s_setprio 1
	s_waitcnt lgkmcnt(6)
	v_mfma_f32_32x32x16_bf16 v[114:129], v[206:209], v[222:225], v[114:129]
	v_mfma_f32_32x32x16_bf16 v[98:113], v[206:209], v[226:229], v[98:113]
	v_mfma_f32_32x32x16_bf16 v[82:97], v[210:213], v[222:225], v[82:97]
	v_mfma_f32_32x32x16_bf16 v[66:81], v[210:213], v[226:229], v[66:81]
	v_mfma_f32_32x32x16_bf16 v[50:65], v[214:217], v[222:225], v[50:65]
	v_mfma_f32_32x32x16_bf16 v[34:49], v[214:217], v[226:229], v[34:49]
	v_mfma_f32_32x32x16_bf16 v[18:33], v[218:221], v[222:225], v[18:33]
	v_mfma_f32_32x32x16_bf16 v[2:17], v[218:221], v[226:229], v[2:17]
	s_setprio 0
	v_add_u32_e32 v181, s16, v0
	ds_read_b128 v[206:209], v181
	ds_read_b128 v[210:213], v181 offset:4096
	ds_read_b128 v[214:217], v181 offset:8192
	ds_read_b128 v[218:221], v181 offset:12288
	v_add_u32_e32 v181, s15, v0
	ds_read_b128 v[222:225], v181 offset:32768
	ds_read_b128 v[226:229], v181 offset:36864
	s_add_i32 s14, s14, 0x10000
	s_and_b32 s16, s14, 0x10000
	s_add_i32 s15, s16, s23
	s_add_i32 s16, s16, s22
	s_cmp_eq_u32 s14, 0x2b0000
	s_waitcnt vmcnt(0) lgkmcnt(0)
	s_barrier
	s_cbranch_scc1 .Lrot9_tail
	s_setprio 1
	s_add_i32 m0, s14, 0x10000
	s_and_b32 m0, m0, 0x10000
	s_add_i32 m0, m0, s21
	v_mfma_f32_32x32x16_bf16 v[114:129], v[182:185], v[198:201], v[114:129]
	global_load_lds_dwordx4 v[176:177], off
	v_lshl_add_u64 v[176:177], v[176:177], 0, s[4:5]
	s_add_i32 m0, m0, 0x400
	v_mfma_f32_32x32x16_bf16 v[98:113], v[182:185], v[202:205], v[98:113]
	v_mfma_f32_32x32x16_bf16 v[82:97], v[186:189], v[198:201], v[82:97]
	global_load_lds_dwordx4 v[168:169], off
	v_lshl_add_u64 v[168:169], v[168:169], 0, s[4:5]
	s_add_i32 m0, m0, 0x400
	v_mfma_f32_32x32x16_bf16 v[66:81], v[186:189], v[202:205], v[66:81]
	v_mfma_f32_32x32x16_bf16 v[50:65], v[190:193], v[198:201], v[50:65]
	global_load_lds_dwordx4 v[166:167], off
	v_lshl_add_u64 v[166:167], v[166:167], 0, s[4:5]
	s_add_i32 m0, m0, 0x400
	v_mfma_f32_32x32x16_bf16 v[34:49], v[190:193], v[202:205], v[34:49]
	v_mfma_f32_32x32x16_bf16 v[18:33], v[194:197], v[198:201], v[18:33]
	global_load_lds_dwordx4 v[164:165], off
	v_lshl_add_u64 v[164:165], v[164:165], 0, s[4:5]
	s_add_i32 m0, m0, 0x7400
	v_mfma_f32_32x32x16_bf16 v[2:17], v[194:197], v[202:205], v[2:17]
	s_setprio 0
	v_add_u32_e32 v181, s16, v178
	ds_read_b128 v[182:185], v181
	ds_read_b128 v[186:189], v181 offset:4096
	ds_read_b128 v[190:193], v181 offset:8192
	ds_read_b128 v[194:197], v181 offset:12288
	v_add_u32_e32 v181, s15, v178
	ds_read_b128 v[198:201], v181 offset:32768
	ds_read_b128 v[202:205], v181 offset:36864
	s_setprio 1
	v_mfma_f32_32x32x16_bf16 v[114:129], v[206:209], v[222:225], v[114:129]
	global_load_lds_dwordx4 v[162:163], off
	v_lshl_add_u64 v[162:163], v[162:163], 0, s[4:5]
	s_add_i32 m0, m0, 0x400
	v_mfma_f32_32x32x16_bf16 v[98:113], v[206:209], v[226:229], v[98:113]
	v_mfma_f32_32x32x16_bf16 v[82:97], v[210:213], v[222:225], v[82:97]
	global_load_lds_dwordx4 v[160:161], off
	v_lshl_add_u64 v[160:161], v[160:161], 0, s[4:5]
	s_add_i32 m0, m0, 0x400
	v_mfma_f32_32x32x16_bf16 v[66:81], v[210:213], v[226:229], v[66:81]
	v_mfma_f32_32x32x16_bf16 v[50:65], v[214:217], v[222:225], v[50:65]
	global_load_lds_dwordx4 v[158:159], off
	v_lshl_add_u64 v[158:159], v[158:159], 0, s[4:5]
	s_add_i32 m0, m0, 0x400
	v_mfma_f32_32x32x16_bf16 v[34:49], v[214:217], v[226:229], v[34:49]
	v_mfma_f32_32x32x16_bf16 v[18:33], v[218:221], v[222:225], v[18:33]
	global_load_lds_dwordx4 v[156:157], off
	v_lshl_add_u64 v[156:157], v[156:157], 0, s[4:5]
	v_mfma_f32_32x32x16_bf16 v[2:17], v[218:221], v[226:229], v[2:17]
	s_setprio 0
	v_add_u32_e32 v181, s16, v175
	ds_read_b128 v[206:209], v181
	ds_read_b128 v[210:213], v181 offset:4096
	ds_read_b128 v[214:217], v181 offset:8192
	ds_read_b128 v[218:221], v181 offset:12288
	v_add_u32_e32 v181, s15, v175
	ds_read_b128 v[222:225], v181 offset:32768
	ds_read_b128 v[226:229], v181 offset:36864
	s_branch .Lrot9_loop

; DI float bflo(unsigned u) { return __uint_as_float(u << 16); }
; DI float bfhi(unsigned u) { return __uint_as_float(u & 0xffff0000u); }
; DI void rowpass(const int wave_s, const float* __restrict__ xin, u16* __restrict__ X, const u16* __restrict__ Y, const float* __restrict__ gpost,
;                 const float* __restrict__ gpre, u16* __restrict__ HN, float* __restrict__ outf) {
;     ...
;     if (Y) {
;       float4 y[4];
;       float ss = 0.f;
; #pragma unroll
;       for (int j = 0; j < 4; ++j) {
;         const uint2 yu = *(const uint2*)(Y + (size_t)row * 1024 + j * 256 + lane * 4);
;         y[j] = make_float4(bflo(yu.x), bfhi(yu.x), bflo(yu.y), bfhi(yu.y));
;         ss += y[j].x * y[j].x + y[j].y * y[j].y + y[j].z * y[j].z + y[j].w * y[j].w;
;       }
;       ss = wsum(ss);
;       const float rs = rsqrtf(ss * (1.f / 1024.f) + 1e-6f);
; #pragma unroll
;       for (int j = 0; j < 4; ++j) {
;         const float4 g = *(const float4*)(gpost + j * 256 + lane * 4);
;         const uint2 xu = *(const uint2*)(X + (size_t)row * 1024 + j * 256 + lane * 4);
;         x[j] = make_float4(bflo(xu.x), bfhi(xu.x), bflo(xu.y), bfhi(xu.y));
;         x[j].x += y[j].x * rs * g.x; x[j].y += y[j].y * rs * g.y; x[j].z += y[j].z * rs * g.z; x[j].w += y[j].w * rs * g.w;
;       }
;     } else {
; #pragma unroll
;       for (int j = 0; j < 4; ++j) x[j] = *(const float4*)(xin + (size_t)row * 1024 + j * 256 + lane * 4);
;     }
;     float ss2 = 0.f;
; #pragma unroll
;     for (int j = 0; j < 4; ++j) {
;       if (outf) *(float4*)(outf + (size_t)row * 1024 + j * 256 + lane * 4) = x[j];
;       else { uint2 xp; xp.x = pack2(x[j].x, x[j].y); xp.y = pack2(x[j].z, x[j].w); *(uint2*)(X + (size_t)row * 1024 + j * 256 + lane * 4) = xp; }
;       ss2 += x[j].x * x[j].x + x[j].y * x[j].y + x[j].z * x[j].z + x[j].w * x[j].w;
;     }
;     if (HN) {
;       ss2 = wsum(ss2);
.LBB0_3761:
	s_ashr_i32 s15, s14, 31
	s_lshl_b64 s[10:11], s[14:15], 11
	v_lshl_add_u64 v[18:19], v[34:35], 0, s[10:11]
	flat_load_dwordx2 v[20:21], v[18:19]
	v_lshl_add_u64 v[44:45], v[36:37], 0, s[10:11]
	flat_load_dwordx2 v[50:51], v[44:45]
	s_lshl_b64 s[4:5], s[14:15], 12
	flat_load_dwordx2 v[52:53], v[44:45] offset:512
	s_waitcnt vmcnt(0) lgkmcnt(0)
	v_lshlrev_b32_e32 v22, 16, v20
	v_and_b32_e32 v23, 0xffff0000, v20
	v_lshlrev_b32_e32 v24, 16, v21
	v_and_b32_e32 v25, 0xffff0000, v21
	flat_load_dwordx2 v[20:21], v[18:19] offset:512
	v_mov_b32_e32 v62, v23
	v_mov_b32_e32 v58, v22
	v_lshlrev_b32_e32 v56, 16, v50
	v_and_b32_e32 v57, 0xffff0000, v50
	v_lshlrev_b32_e32 v60, 16, v51
	v_and_b32_e32 v61, 0xffff0000, v51
	v_mov_b32_e32 v50, v24
	v_mov_b32_e32 v54, v25
	s_waitcnt vmcnt(0) lgkmcnt(0)
	v_lshlrev_b32_e32 v26, 16, v20
	v_and_b32_e32 v27, 0xffff0000, v20
	v_lshlrev_b32_e32 v28, 16, v21
	v_and_b32_e32 v29, 0xffff0000, v21
	flat_load_dwordx2 v[20:21], v[18:19] offset:1024
	v_mov_b32_e32 v63, v27
	v_mov_b32_e32 v59, v26
	v_pk_mul_f32 v[62:63], v[62:63], v[62:63]
	v_mov_b32_e32 v51, v28
	v_pk_fma_f32 v[58:59], v[58:59], v[58:59], v[62:63]
	v_mov_b32_e32 v55, v29
	v_pk_fma_f32 v[50:51], v[50:51], v[50:51], v[58:59]
	s_waitcnt vmcnt(0) lgkmcnt(0)
	v_lshlrev_b32_e32 v30, 16, v20
	v_and_b32_e32 v46, 0xffff0000, v20
	v_lshlrev_b32_e32 v32, 16, v21
	v_and_b32_e32 v48, 0xffff0000, v21
	flat_load_dwordx2 v[20:21], v[18:19] offset:1536
	v_pk_fma_f32 v[58:59], v[54:55], v[54:55], v[50:51]
	flat_load_dwordx2 v[54:55], v[44:45] offset:1024
	flat_load_dwordx2 v[50:51], v[44:45] offset:1536
	v_add_f32_e32 v0, v58, v59
	s_waitcnt vmcnt(0) lgkmcnt(0)
	v_and_b32_e32 v19, 0xffff0000, v20
	v_lshlrev_b32_e32 v18, 16, v20
	v_mov_b32_e32 v47, v19
	v_lshlrev_b32_e32 v20, 16, v21
	v_mov_b32_e32 v31, v18
	v_pk_mul_f32 v[62:63], v[46:47], v[46:47]
	v_and_b32_e32 v21, 0xffff0000, v21
	v_mov_b32_e32 v33, v20
	v_pk_fma_f32 v[62:63], v[30:31], v[30:31], v[62:63]
	v_mov_b32_e32 v49, v21
	v_pk_fma_f32 v[62:63], v[32:33], v[32:33], v[62:63]
	s_nop 0
	v_pk_fma_f32 v[62:63], v[48:49], v[48:49], v[62:63]
	s_nop 0
	v_add_f32_e32 v0, v0, v62
	v_add_f32_e32 v0, v0, v63
	v_mov_b32_e32 v31, v0
	s_nop 1
	v_permlane32_swap_b32_e32 v0, v31
	s_waitcnt lgkmcnt(0)
	v_add_f32_e32 v0, v0, v31
	v_mov_b32_e32 v31, v0
	s_nop 1
	v_permlane16_swap_b32_e32 v0, v31
	s_waitcnt lgkmcnt(0)
	v_add_f32_e32 v0, v0, v31
	s_nop 1
	v_mov_b32_dpp v31, v0 row_ror:8 row_mask:0xf bank_mask:0xf
	s_waitcnt lgkmcnt(0)
	v_add_f32_e32 v0, v0, v31
	s_nop 1
	v_mov_b32_dpp v31, v0 row_ror:4 row_mask:0xf bank_mask:0xf
	s_waitcnt lgkmcnt(0)
	v_add_f32_e32 v0, v0, v31
	s_nop 1
	v_mov_b32_dpp v31, v0 row_ror:2 row_mask:0xf bank_mask:0xf
	s_waitcnt lgkmcnt(0)
	v_add_f32_e32 v0, v0, v31
	s_nop 1
	v_mov_b32_dpp v31, v0 row_ror:1 row_mask:0xf bank_mask:0xf
	s_waitcnt lgkmcnt(0)
	v_add_f32_e32 v0, v0, v31
	v_fmamk_f32 v0, v0, 0x3a800000, v170
	v_cmp_gt_f32_e32 vcc, s33, v0
	v_mul_f32_e32 v31, 0x4b800000, v0
	s_nop 0
	v_cndmask_b32_e32 v0, v0, v31, vcc
	v_rsq_f32_e32 v0, v0
	s_nop 0
	v_mul_f32_e32 v31, 0x45800000, v0
	v_cndmask_b32_e32 v58, v0, v31, vcc
	v_pk_mul_f32 v[22:23], v[58:59], v[22:23] op_sel_hi:[0,1]
	v_pk_mul_f32 v[24:25], v[58:59], v[24:25] op_sel_hi:[0,1]
	v_cndmask_b32_e64 v0, 0, 1, s[0:1]
	v_pk_fma_f32 v[22:23], v[10:11], v[22:23], v[56:57]
	v_pk_fma_f32 v[24:25], v[12:13], v[24:25], v[60:61]
	v_lshl_add_u64 v[56:57], v[38:39], 0, s[4:5]
	v_cmp_ne_u32_e64 s[4:5], 1, v0
	s_andn2_b64 vcc, exec, s[0:1]
	s_cbranch_vccnz .LBB0_3775
	global_store_dwordx4 v[56:57], v[22:25], off
	s_cbranch_execnz .LBB0_3764

; DI void rowpass(const int wave_s, const float* __restrict__ xin, u16* __restrict__ X, const u16* __restrict__ Y, const float* __restrict__ gpost,
;                 const float* __restrict__ gpre, u16* __restrict__ HN, float* __restrict__ outf) {
;     ...
;     if (HN) {
;       ss2 = wsum(ss2);
;       const float rs2 = rsqrtf(ss2 * (1.f / 1024.f) + 1e-6f);
; #pragma unroll
;       for (int j = 0; j < 4; ++j) {
;         const float4 g = *(const float4*)(gpre + j * 256 + lane * 4);
;         uint2 pk;
;         pk.x = pack2(x[j].x * rs2 * g.x, x[j].y * rs2 * g.y);
;         pk.y = pack2(x[j].z * rs2 * g.z, x[j].w * rs2 * g.w);
;         *(uint2*)(HN + (size_t)row * 1024 + j * 256 + lane * 4) = pk;
;       }
.LBB0_3773:
	s_andn2_b64 vcc, exec, s[8:9]
	s_cbranch_vccnz .LBB0_3760
	v_pk_mul_f32 v[44:45], v[22:23], v[22:23]
	v_pk_mul_f32 v[46:47], v[24:25], v[24:25]
	v_add_f32_e32 v44, v44, v45
	v_pk_mul_f32 v[48:49], v[26:27], v[26:27]
	v_add_f32_e32 v44, v46, v44
	v_add_f32_e32 v0, v48, v49
	v_add_f32_e32 v44, v47, v44
	flat_load_dwordx4 v[46:49], v[40:41]
	v_pk_mul_f32 v[50:51], v[28:29], v[28:29]
	v_pk_mul_f32 v[52:53], v[30:31], v[30:31]
	v_add_f32_e32 v0, v50, v0
	v_add_f32_e32 v0, v51, v0
	v_pk_mul_f32 v[54:55], v[32:33], v[32:33]
	v_add_f32_e32 v0, v44, v0
	v_add_f32_e32 v44, v52, v53
	v_add_f32_e32 v44, v44, v54
	v_pk_mul_f32 v[56:57], v[18:19], v[18:19]
	v_add_f32_e32 v44, v55, v44
	v_pk_mul_f32 v[58:59], v[20:21], v[20:21]
	v_add_f32_e32 v0, v0, v44
	v_add_f32_e32 v44, v56, v57
	v_add_f32_e32 v44, v44, v58
	v_add_f32_e32 v44, v59, v44
	v_add_f32_e32 v0, v0, v44
	v_mov_b32_e32 v44, v0
	s_nop 1
	v_permlane32_swap_b32_e32 v0, v44
	s_waitcnt lgkmcnt(0)
	v_add_f32_e32 v0, v0, v44
	v_mov_b32_e32 v44, v0
	s_nop 1
	v_permlane16_swap_b32_e32 v0, v44
	s_waitcnt lgkmcnt(0)
	v_add_f32_e32 v0, v0, v44
	s_nop 1
	v_mov_b32_dpp v44, v0 row_ror:8 row_mask:0xf bank_mask:0xf
	s_waitcnt lgkmcnt(0)
	v_add_f32_e32 v0, v0, v44
	s_nop 1
	v_mov_b32_dpp v44, v0 row_ror:4 row_mask:0xf bank_mask:0xf
	s_waitcnt lgkmcnt(0)
	v_add_f32_e32 v0, v0, v44
	s_nop 1
	v_mov_b32_dpp v44, v0 row_ror:2 row_mask:0xf bank_mask:0xf
	s_waitcnt lgkmcnt(0)
	v_add_f32_e32 v0, v0, v44
	s_nop 1
	v_mov_b32_dpp v44, v0 row_ror:1 row_mask:0xf bank_mask:0xf
	s_waitcnt lgkmcnt(0)
	v_add_f32_e32 v0, v0, v44
	v_fmamk_f32 v0, v0, 0x3a800000, v170
	v_cmp_gt_f32_e32 vcc, s33, v0
	v_mul_f32_e32 v44, 0x4b800000, v0
	s_nop 0
	v_cndmask_b32_e32 v0, v0, v44, vcc
	v_rsq_f32_e32 v0, v0
	s_nop 0
	v_mul_f32_e32 v44, 0x45800000, v0
	v_cndmask_b32_e32 v0, v0, v44, vcc
	v_pk_mul_f32 v[22:23], v[22:23], v[0:1] op_sel_hi:[1,0]
	v_pk_mul_f32 v[24:25], v[24:25], v[0:1] op_sel_hi:[1,0]
	v_lshl_add_u64 v[44:45], v[42:43], 0, s[10:11]
	v_pk_mul_f32 v[26:27], v[26:27], v[0:1] op_sel_hi:[1,0]
	v_pk_mul_f32 v[18:19], v[18:19], v[0:1] op_sel_hi:[1,0]
	v_pk_mul_f32 v[20:21], v[20:21], v[0:1] op_sel_hi:[1,0]
	s_waitcnt vmcnt(0)
	v_pk_mul_f32 v[22:23], v[46:47], v[22:23]
	v_pk_mul_f32 v[24:25], v[48:49], v[24:25]
	v_cvt_pk_bf16_f32 v22, v22, v23
	v_cvt_pk_bf16_f32 v23, v24, v25
	flat_store_dwordx2 v[44:45], v[22:23]
	flat_load_dwordx4 v[22:25], v[40:41] offset:1024
	s_waitcnt vmcnt(0) lgkmcnt(0)
	v_pk_mul_f32 v[22:23], v[22:23], v[26:27]
	v_pk_mul_f32 v[26:27], v[28:29], v[0:1] op_sel_hi:[1,0]
	v_cvt_pk_bf16_f32 v22, v22, v23
	v_pk_mul_f32 v[24:25], v[24:25], v[26:27]
	v_pk_mul_f32 v[26:27], v[30:31], v[0:1] op_sel_hi:[1,0]
	v_cvt_pk_bf16_f32 v23, v24, v25
	flat_store_dwordx2 v[44:45], v[22:23] offset:512
	flat_load_dwordx4 v[22:25], v[40:41] offset:2048
	s_waitcnt vmcnt(0) lgkmcnt(0)
	v_pk_mul_f32 v[22:23], v[26:27], v[22:23]
	v_pk_mul_f32 v[26:27], v[32:33], v[0:1] op_sel_hi:[1,0]
	v_cvt_pk_bf16_f32 v22, v22, v23
	v_pk_mul_f32 v[24:25], v[26:27], v[24:25]
	s_nop 0
	v_cvt_pk_bf16_f32 v23, v24, v25
	flat_store_dwordx2 v[44:45], v[22:23] offset:1024
	flat_load_dwordx4 v[22:25], v[40:41] offset:3072
	s_waitcnt vmcnt(0) lgkmcnt(0)
	v_pk_mul_f32 v[18:19], v[18:19], v[22:23]
	v_pk_mul_f32 v[20:21], v[20:21], v[24:25]
	v_cvt_pk_bf16_f32 v18, v18, v19
	v_cvt_pk_bf16_f32 v19, v20, v21
	flat_store_dwordx2 v[44:45], v[18:19] offset:1536
	s_branch .LBB0_3760
